# attention unit ping-pong: waves 0-3 and 4-7 run MFMA (PV+next QK) and softmax segments on alternate barrier slots, software-pipelined PV, packed P in place
# baseline (speedup 1.0000x reference)
.Lam_go:
	s_bfe_u32 s14, s46, 0x10001
	s_lshl_b32 s15, s12, 9
	s_lshl_b32 s28, s14, 8
	s_add_i32 s28, s28, s15
	s_lshl_b32 s8, s10, 12
	s_add_i32 s8, s8, s28
	s_add_u32 s16, s40, s8
	s_addc_u32 s17, s41, 0
	s_lshl_b32 s8, s11, 12
	s_add_i32 s9, s8, s28
	s_add_u32 s18, s42, s9
	s_addc_u32 s19, s43, 0
	s_add_i32 s9, s8, s15
	s_add_u32 s20, s44, s9
	s_addc_u32 s21, s45, 0
	s_lshl_b32 s8, s10, 13
	s_lshl_b32 s9, s28, 1
	s_add_i32 s8, s8, s9
	s_add_u32 s22, s48, s8
	s_addc_u32 s23, s49, 0
	v_mbcnt_lo_u32_b32 v96, -1, 0
	v_mbcnt_hi_u32_b32 v96, -1, v96
	s_lshr_b32 s36, s84, 6
	s_lshl_b32 s38, s36, 3
	s_lshl_b32 s39, s36, 11
	s_lshl_b32 s47, s36, 12
	s_add_i32 s47, s47, 0x4000
	s_lshl_b32 s50, s36, 8
	s_add_i32 s50, s50, 0x18000
	v_and_b32_e32 v240, 31, v96
	v_lshrrev_b32_e32 v241, 5, v96
	s_lshl_b32 s37, s36, 5
	v_add_u32_e32 v242, s37, v240
	v_lshlrev_b32_e32 v242, 12, v242
	v_lshl_add_u32 v242, v241, 4, v242
	global_load_dwordx4 v[130:133], v242, s[16:17]
	global_load_dwordx4 v[134:137], v242, s[16:17] offset:32
	global_load_dwordx4 v[138:141], v242, s[16:17] offset:64
	global_load_dwordx4 v[142:145], v242, s[16:17] offset:96
	global_load_dwordx4 v[146:149], v242, s[16:17] offset:128
	global_load_dwordx4 v[150:153], v242, s[16:17] offset:160
	global_load_dwordx4 v[154:157], v242, s[16:17] offset:192
	global_load_dwordx4 v[158:161], v242, s[16:17] offset:224
	v_lshlrev_b32_e32 v243, 8, v240
	v_and_b32_e32 v238, 7, v240
	v_lshlrev_b32_e32 v238, 4, v238
	v_lshlrev_b32_e32 v239, 4, v241
	v_mov_b32_e32 v228, v239
	v_xor_b32_e32 v228, v228, v238
	v_add_u32_e32 v228, v228, v243
	v_or_b32_e32 v229, 32, v239
	v_xor_b32_e32 v229, v229, v238
	v_add_u32_e32 v229, v229, v243
	v_or_b32_e32 v230, 64, v239
	v_xor_b32_e32 v230, v230, v238
	v_add_u32_e32 v230, v230, v243
	v_or_b32_e32 v231, 96, v239
	v_xor_b32_e32 v231, v231, v238
	v_add_u32_e32 v231, v231, v243
	v_or_b32_e32 v232, 128, v239
	v_xor_b32_e32 v232, v232, v238
	v_add_u32_e32 v232, v232, v243
	v_or_b32_e32 v233, 160, v239
	v_xor_b32_e32 v233, v233, v238
	v_add_u32_e32 v233, v233, v243
	v_or_b32_e32 v234, 192, v239
	v_xor_b32_e32 v234, v234, v238
	v_add_u32_e32 v234, v234, v243
	v_or_b32_e32 v235, 224, v239
	v_xor_b32_e32 v235, v235, v238
	v_add_u32_e32 v235, v235, v243
	v_and_b32_e32 v238, 3, v96
	v_lshlrev_b32_e32 v236, 3, v238
	v_bfe_u32 v238, v96, 2, 2
	v_lshl_or_b32 v236, v238, 6, v236
	v_bfe_u32 v238, v96, 4, 1
	v_lshl_or_b32 v236, v238, 5, v236
	v_lshl_or_b32 v236, v241, 8, v236
	v_add_u32_e32 v237, 0x10000, v236
	v_add_u32_e32 v236, 0x4000, v236
	v_lshrrev_b32_e32 v238, 4, v96
	v_and_b32_e32 v239, 15, v96
	v_add_u32_e32 v243, 0, v238
	v_xor_b32_e32 v244, v239, v243
	v_lshlrev_b32_e32 v244, 4, v244
	v_add_u32_e32 v243, s38, v243
	v_lshl_add_u32 v244, v243, 12, v244
	v_add_u32_e32 v243, 4, v238
	v_xor_b32_e32 v245, v239, v243
	v_lshlrev_b32_e32 v245, 4, v245
	v_add_u32_e32 v243, s38, v243
	v_lshl_add_u32 v245, v243, 12, v245
	v_lshrrev_b32_e32 v238, 2, v240
	v_add_u32_e32 v238, s38, v238
	v_and_b32_e32 v239, 0xfffffff3, v238
	v_and_b32_e32 v243, 4, v238
	v_lshl_or_b32 v239, v243, 1, v239
	v_and_b32_e32 v243, 8, v238
	v_lshrrev_b32_e32 v243, 1, v243
	v_or_b32_e32 v239, v239, v243
	v_lshlrev_b32_e32 v239, 12, v239
	v_and_b32_e32 v238, 3, v240
	v_lshlrev_b32_e32 v238, 4, v238
	v_add_u32_e32 v243, 0, v241
	v_lshl_add_u32 v243, v243, 6, v238
	v_add_u32_e32 v246, v239, v243
	v_add_u32_e32 v243, 2, v241
	v_lshl_add_u32 v243, v243, 6, v238
	v_add_u32_e32 v247, v239, v243
	v_add_u32_e32 v243, 4, v241
	v_lshl_add_u32 v243, v243, 6, v238
	v_add_u32_e32 v248, v239, v243
	v_add_u32_e32 v243, 6, v241
	v_lshl_add_u32 v243, v243, 6, v238
	v_add_u32_e32 v249, v239, v243
	v_mov_b32_e32 v238, 0xf149f2ca
	v_mov_b32_e32 v239, 0
	v_mov_b32_e32 v0, 0
	v_mov_b32_e32 v1, 0
	v_mov_b32_e32 v2, 0
	v_mov_b32_e32 v3, 0
	v_mov_b32_e32 v4, 0
	v_mov_b32_e32 v5, 0
	v_mov_b32_e32 v6, 0
	v_mov_b32_e32 v7, 0
	v_mov_b32_e32 v8, 0
	v_mov_b32_e32 v9, 0
	v_mov_b32_e32 v10, 0
	v_mov_b32_e32 v11, 0
	v_mov_b32_e32 v12, 0
	v_mov_b32_e32 v13, 0
	v_mov_b32_e32 v14, 0
	v_mov_b32_e32 v15, 0
	v_mov_b32_e32 v16, 0
	v_mov_b32_e32 v17, 0
	v_mov_b32_e32 v18, 0
	v_mov_b32_e32 v19, 0
	v_mov_b32_e32 v20, 0
	v_mov_b32_e32 v21, 0
	v_mov_b32_e32 v22, 0
	v_mov_b32_e32 v23, 0
	v_mov_b32_e32 v24, 0
	v_mov_b32_e32 v25, 0
	v_mov_b32_e32 v26, 0
	v_mov_b32_e32 v27, 0
	v_mov_b32_e32 v28, 0
	v_mov_b32_e32 v29, 0
	v_mov_b32_e32 v30, 0
	v_mov_b32_e32 v31, 0
	v_mov_b32_e32 v32, 0
	v_mov_b32_e32 v33, 0
	v_mov_b32_e32 v34, 0
	v_mov_b32_e32 v35, 0
	v_mov_b32_e32 v36, 0
	v_mov_b32_e32 v37, 0
	v_mov_b32_e32 v38, 0
	v_mov_b32_e32 v39, 0
	v_mov_b32_e32 v40, 0
	v_mov_b32_e32 v41, 0
	v_mov_b32_e32 v42, 0
	v_mov_b32_e32 v43, 0
	v_mov_b32_e32 v44, 0
	v_mov_b32_e32 v45, 0
	v_mov_b32_e32 v46, 0
	v_mov_b32_e32 v47, 0
	v_mov_b32_e32 v48, 0
	v_mov_b32_e32 v49, 0
	v_mov_b32_e32 v50, 0
	v_mov_b32_e32 v51, 0
	v_mov_b32_e32 v52, 0
	v_mov_b32_e32 v53, 0
	v_mov_b32_e32 v54, 0
	v_mov_b32_e32 v55, 0
	v_mov_b32_e32 v56, 0
	v_mov_b32_e32 v57, 0
	v_mov_b32_e32 v58, 0
	v_mov_b32_e32 v59, 0
	v_mov_b32_e32 v60, 0
	v_mov_b32_e32 v61, 0
	v_mov_b32_e32 v62, 0
	v_mov_b32_e32 v63, 0
	v_mov_b32_e32 v64, 0
	v_mov_b32_e32 v65, 0
	v_mov_b32_e32 v66, 0
	v_mov_b32_e32 v67, 0
	v_mov_b32_e32 v68, 0
	v_mov_b32_e32 v69, 0
	v_mov_b32_e32 v70, 0
	v_mov_b32_e32 v71, 0
	v_mov_b32_e32 v72, 0
	v_mov_b32_e32 v73, 0
	v_mov_b32_e32 v74, 0
	v_mov_b32_e32 v75, 0
	v_mov_b32_e32 v76, 0
	v_mov_b32_e32 v77, 0
	v_mov_b32_e32 v78, 0
	v_mov_b32_e32 v79, 0
	v_mov_b32_e32 v80, 0
	v_mov_b32_e32 v81, 0
	v_mov_b32_e32 v82, 0
	v_mov_b32_e32 v83, 0
	v_mov_b32_e32 v84, 0
	v_mov_b32_e32 v85, 0
	v_mov_b32_e32 v86, 0
	v_mov_b32_e32 v87, 0
	v_mov_b32_e32 v88, 0
	v_mov_b32_e32 v89, 0
	v_mov_b32_e32 v90, 0
	v_mov_b32_e32 v91, 0
	v_mov_b32_e32 v92, 0
	v_mov_b32_e32 v93, 0
	v_mov_b32_e32 v94, 0
	v_mov_b32_e32 v95, 0
	v_mov_b32_e32 v98, 0
	v_mov_b32_e32 v99, 0
	v_mov_b32_e32 v100, 0
	v_mov_b32_e32 v101, 0
	v_mov_b32_e32 v102, 0
	v_mov_b32_e32 v103, 0
	v_mov_b32_e32 v104, 0
	v_mov_b32_e32 v105, 0
	v_mov_b32_e32 v106, 0
	v_mov_b32_e32 v107, 0
	v_mov_b32_e32 v108, 0
	v_mov_b32_e32 v109, 0
	v_mov_b32_e32 v110, 0
	v_mov_b32_e32 v111, 0
	v_mov_b32_e32 v112, 0
	v_mov_b32_e32 v113, 0
	v_mov_b32_e32 v114, 0
	v_mov_b32_e32 v115, 0
	v_mov_b32_e32 v116, 0
	v_mov_b32_e32 v117, 0
	v_mov_b32_e32 v118, 0
	v_mov_b32_e32 v119, 0
	v_mov_b32_e32 v120, 0
	v_mov_b32_e32 v121, 0
	v_mov_b32_e32 v122, 0
	v_mov_b32_e32 v123, 0
	v_mov_b32_e32 v124, 0
	v_mov_b32_e32 v125, 0
	v_mov_b32_e32 v126, 0
	v_mov_b32_e32 v127, 0
	v_mov_b32_e32 v128, 0
	v_mov_b32_e32 v129, 0
	s_add_i32 m0, s39, 0x0
	s_nop 0
	global_load_lds_dwordx4 v244, s[18:19]
	s_add_i32 m0, s39, 0x400
	s_nop 0
	global_load_lds_dwordx4 v245, s[18:19]
	s_add_u32 s18, s18, 0x40000
	s_addc_u32 s19, s19, 0
	s_waitcnt vmcnt(0)
	s_barrier
	s_cmp_ge_u32 s36, 4
	s_cbranch_scc1 .Lap_B
	s_add_i32 m0, s47, 0x0
	s_nop 0
	global_load_lds_dwordx4 v246, s[20:21]
	s_add_i32 m0, s47, 0x400
	s_nop 0
	global_load_lds_dwordx4 v247, s[20:21]
	s_add_i32 m0, s47, 0x800
	s_nop 0
	global_load_lds_dwordx4 v248, s[20:21]
	s_add_i32 m0, s47, 0xc00
	s_nop 0
	global_load_lds_dwordx4 v249, s[20:21]
	s_add_u32 s20, s20, 0x40000
	s_addc_u32 s21, s21, 0
	s_add_i32 m0, s39, 0xc000
	s_nop 0
	global_load_lds_dwordx4 v244, s[18:19]
	s_add_i32 m0, s39, 0xc400
	s_nop 0
	global_load_lds_dwordx4 v245, s[18:19]
	s_add_u32 s18, s18, 0x40000
	s_addc_u32 s19, s19, 0
	ds_read_b128 v[212:215], v228 offset:0
	ds_read_b128 v[216:219], v228 offset:8192
	ds_read_b128 v[220:223], v229 offset:0
	ds_read_b128 v[224:227], v229 offset:8192
	s_waitcnt lgkmcnt(2)
	v_mfma_f32_32x32x16_bf16 v[162:177], v[212:215], v[130:133], 0
	v_mfma_f32_32x32x16_bf16 v[178:193], v[216:219], v[130:133], 0
	ds_read_b128 v[212:215], v230 offset:0
	ds_read_b128 v[216:219], v230 offset:8192
	s_waitcnt lgkmcnt(2)
	v_mfma_f32_32x32x16_bf16 v[162:177], v[220:223], v[134:137], v[162:177]
	v_mfma_f32_32x32x16_bf16 v[178:193], v[224:227], v[134:137], v[178:193]
	ds_read_b128 v[220:223], v231 offset:0
	ds_read_b128 v[224:227], v231 offset:8192
	s_waitcnt lgkmcnt(2)
	v_mfma_f32_32x32x16_bf16 v[162:177], v[212:215], v[138:141], v[162:177]
	v_mfma_f32_32x32x16_bf16 v[178:193], v[216:219], v[138:141], v[178:193]
	ds_read_b128 v[212:215], v232 offset:0
	ds_read_b128 v[216:219], v232 offset:8192
	s_waitcnt lgkmcnt(2)
	v_mfma_f32_32x32x16_bf16 v[162:177], v[220:223], v[142:145], v[162:177]
	v_mfma_f32_32x32x16_bf16 v[178:193], v[224:227], v[142:145], v[178:193]
	ds_read_b128 v[220:223], v233 offset:0
	ds_read_b128 v[224:227], v233 offset:8192
	s_waitcnt lgkmcnt(2)
	v_mfma_f32_32x32x16_bf16 v[162:177], v[212:215], v[146:149], v[162:177]
	v_mfma_f32_32x32x16_bf16 v[178:193], v[216:219], v[146:149], v[178:193]
	ds_read_b128 v[212:215], v234 offset:0
	ds_read_b128 v[216:219], v234 offset:8192
	s_waitcnt lgkmcnt(2)
	v_mfma_f32_32x32x16_bf16 v[162:177], v[220:223], v[150:153], v[162:177]
	v_mfma_f32_32x32x16_bf16 v[178:193], v[224:227], v[150:153], v[178:193]
	ds_read_b128 v[220:223], v235 offset:0
	ds_read_b128 v[224:227], v235 offset:8192
	s_waitcnt lgkmcnt(2)
	v_mfma_f32_32x32x16_bf16 v[162:177], v[212:215], v[154:157], v[162:177]
	v_mfma_f32_32x32x16_bf16 v[178:193], v[216:219], v[154:157], v[178:193]
	s_waitcnt lgkmcnt(0)
	v_mfma_f32_32x32x16_bf16 v[162:177], v[220:223], v[158:161], v[162:177]
	v_mfma_f32_32x32x16_bf16 v[178:193], v[224:227], v[158:161], v[178:193]
	s_nop 7
	s_nop 4
	s_barrier
.Lap_loopA:
	v_max_f32_e32 v240, v162, v163
	v_max3_f32 v240, v240, v164, v165
	v_max3_f32 v240, v240, v166, v167
	v_max3_f32 v240, v240, v168, v169
	v_max3_f32 v240, v240, v170, v171
	v_max3_f32 v240, v240, v172, v173
	v_max3_f32 v240, v240, v174, v175
	v_max3_f32 v240, v240, v176, v177
	v_max3_f32 v240, v240, v178, v179
	v_max3_f32 v240, v240, v180, v181
	v_max3_f32 v240, v240, v182, v183
	v_max3_f32 v240, v240, v184, v185
	v_max3_f32 v240, v240, v186, v187
	v_max3_f32 v240, v240, v188, v189
	v_max3_f32 v240, v240, v190, v191
	v_max3_f32 v240, v240, v192, v193
	v_mov_b32_e32 v241, v240
	s_nop 1
	v_permlane32_swap_b32_e32 v240, v241
	v_max_f32_e32 v240, v240, v241
	v_sub_f32_e32 v241, v240, v238
	v_cmp_ge_f32_e32 vcc, 0x42b504f3, v241
	s_nop 3
	s_cmp_eq_u64 vcc, exec
	s_cbranch_scc1 .Lap_keep_A0
	v_max_f32_e32 v240, v238, v240
	v_sub_f32_e32 v241, v238, v240
	v_mul_f32_e32 v241, 0x3e0293ee, v241
	v_exp_f32_e32 v242, v241
	v_mov_b32_e32 v238, v240
	v_and_b32_e32 v240, 31, v96
	v_lshl_add_u32 v240, v240, 2, s50
	v_mul_f32_e32 v239, v239, v242
	ds_write_b32 v240, v242
	v_lshrrev_b32_e32 v240, 5, v96
	v_lshl_add_u32 v240, v240, 4, s50
	s_waitcnt lgkmcnt(0)
	ds_read_b128 v[212:215], v240 offset:0
	ds_read_b128 v[216:219], v240 offset:32
	ds_read_b128 v[220:223], v240 offset:64
	ds_read_b128 v[224:227], v240 offset:96
	s_waitcnt lgkmcnt(0)
	v_pk_mul_f32 v[0:1], v[0:1], v[212:213]
	v_pk_mul_f32 v[2:3], v[2:3], v[214:215]
	v_pk_mul_f32 v[4:5], v[4:5], v[216:217]
	v_pk_mul_f32 v[6:7], v[6:7], v[218:219]
	v_pk_mul_f32 v[8:9], v[8:9], v[220:221]
	v_pk_mul_f32 v[10:11], v[10:11], v[222:223]
	v_pk_mul_f32 v[12:13], v[12:13], v[224:225]
	v_pk_mul_f32 v[14:15], v[14:15], v[226:227]
	v_pk_mul_f32 v[16:17], v[16:17], v[212:213]
	v_pk_mul_f32 v[18:19], v[18:19], v[214:215]
	v_pk_mul_f32 v[20:21], v[20:21], v[216:217]
	v_pk_mul_f32 v[22:23], v[22:23], v[218:219]
	v_pk_mul_f32 v[24:25], v[24:25], v[220:221]
	v_pk_mul_f32 v[26:27], v[26:27], v[222:223]
	v_pk_mul_f32 v[28:29], v[28:29], v[224:225]
	v_pk_mul_f32 v[30:31], v[30:31], v[226:227]
	v_pk_mul_f32 v[32:33], v[32:33], v[212:213]
	v_pk_mul_f32 v[34:35], v[34:35], v[214:215]
	v_pk_mul_f32 v[36:37], v[36:37], v[216:217]
	v_pk_mul_f32 v[38:39], v[38:39], v[218:219]
	v_pk_mul_f32 v[40:41], v[40:41], v[220:221]
	v_pk_mul_f32 v[42:43], v[42:43], v[222:223]
	v_pk_mul_f32 v[44:45], v[44:45], v[224:225]
	v_pk_mul_f32 v[46:47], v[46:47], v[226:227]
	v_pk_mul_f32 v[48:49], v[48:49], v[212:213]
	v_pk_mul_f32 v[50:51], v[50:51], v[214:215]
	v_pk_mul_f32 v[52:53], v[52:53], v[216:217]
	v_pk_mul_f32 v[54:55], v[54:55], v[218:219]
	v_pk_mul_f32 v[56:57], v[56:57], v[220:221]
	v_pk_mul_f32 v[58:59], v[58:59], v[222:223]
	v_pk_mul_f32 v[60:61], v[60:61], v[224:225]
	v_pk_mul_f32 v[62:63], v[62:63], v[226:227]
	v_pk_mul_f32 v[64:65], v[64:65], v[212:213]
	v_pk_mul_f32 v[66:67], v[66:67], v[214:215]
	v_pk_mul_f32 v[68:69], v[68:69], v[216:217]
	v_pk_mul_f32 v[70:71], v[70:71], v[218:219]
	v_pk_mul_f32 v[72:73], v[72:73], v[220:221]
	v_pk_mul_f32 v[74:75], v[74:75], v[222:223]
	v_pk_mul_f32 v[76:77], v[76:77], v[224:225]
	v_pk_mul_f32 v[78:79], v[78:79], v[226:227]
	v_pk_mul_f32 v[80:81], v[80:81], v[212:213]
	v_pk_mul_f32 v[82:83], v[82:83], v[214:215]
	v_pk_mul_f32 v[84:85], v[84:85], v[216:217]
	v_pk_mul_f32 v[86:87], v[86:87], v[218:219]
	v_pk_mul_f32 v[88:89], v[88:89], v[220:221]
	v_pk_mul_f32 v[90:91], v[90:91], v[222:223]
	v_pk_mul_f32 v[92:93], v[92:93], v[224:225]
	v_pk_mul_f32 v[94:95], v[94:95], v[226:227]
	v_pk_mul_f32 v[98:99], v[98:99], v[212:213]
	v_pk_mul_f32 v[100:101], v[100:101], v[214:215]
	v_pk_mul_f32 v[102:103], v[102:103], v[216:217]
	v_pk_mul_f32 v[104:105], v[104:105], v[218:219]
	v_pk_mul_f32 v[106:107], v[106:107], v[220:221]
	v_pk_mul_f32 v[108:109], v[108:109], v[222:223]
	v_pk_mul_f32 v[110:111], v[110:111], v[224:225]
	v_pk_mul_f32 v[112:113], v[112:113], v[226:227]
	v_pk_mul_f32 v[114:115], v[114:115], v[212:213]
	v_pk_mul_f32 v[116:117], v[116:117], v[214:215]
	v_pk_mul_f32 v[118:119], v[118:119], v[216:217]
	v_pk_mul_f32 v[120:121], v[120:121], v[218:219]
	v_pk_mul_f32 v[122:123], v[122:123], v[220:221]
	v_pk_mul_f32 v[124:125], v[124:125], v[222:223]
	v_pk_mul_f32 v[126:127], v[126:127], v[224:225]
	v_pk_mul_f32 v[128:129], v[128:129], v[226:227]
.Lap_keep_A0:
	v_mul_f32_e32 v243, 0xbe0293ee, v238
	v_fmamk_f32 v162, v162, 0x3e0293ee, v243
	v_fmamk_f32 v163, v163, 0x3e0293ee, v243
	v_fmamk_f32 v164, v164, 0x3e0293ee, v243
	v_fmamk_f32 v165, v165, 0x3e0293ee, v243
	v_fmamk_f32 v166, v166, 0x3e0293ee, v243
	v_fmamk_f32 v167, v167, 0x3e0293ee, v243
	v_fmamk_f32 v168, v168, 0x3e0293ee, v243
	v_fmamk_f32 v169, v169, 0x3e0293ee, v243
	v_fmamk_f32 v170, v170, 0x3e0293ee, v243
	v_fmamk_f32 v171, v171, 0x3e0293ee, v243
	v_fmamk_f32 v172, v172, 0x3e0293ee, v243
	v_fmamk_f32 v173, v173, 0x3e0293ee, v243
	v_fmamk_f32 v174, v174, 0x3e0293ee, v243
	v_fmamk_f32 v175, v175, 0x3e0293ee, v243
	v_fmamk_f32 v176, v176, 0x3e0293ee, v243
	v_fmamk_f32 v177, v177, 0x3e0293ee, v243
	v_fmamk_f32 v178, v178, 0x3e0293ee, v243
	v_fmamk_f32 v179, v179, 0x3e0293ee, v243
	v_fmamk_f32 v180, v180, 0x3e0293ee, v243
	v_fmamk_f32 v181, v181, 0x3e0293ee, v243
	v_fmamk_f32 v182, v182, 0x3e0293ee, v243
	v_fmamk_f32 v183, v183, 0x3e0293ee, v243
	v_fmamk_f32 v184, v184, 0x3e0293ee, v243
	v_fmamk_f32 v185, v185, 0x3e0293ee, v243
	v_fmamk_f32 v186, v186, 0x3e0293ee, v243
	v_fmamk_f32 v187, v187, 0x3e0293ee, v243
	v_fmamk_f32 v188, v188, 0x3e0293ee, v243
	v_fmamk_f32 v189, v189, 0x3e0293ee, v243
	v_fmamk_f32 v190, v190, 0x3e0293ee, v243
	v_fmamk_f32 v191, v191, 0x3e0293ee, v243
	v_fmamk_f32 v192, v192, 0x3e0293ee, v243
	v_fmamk_f32 v193, v193, 0x3e0293ee, v243
	v_exp_f32_e32 v162, v162
	v_exp_f32_e32 v163, v163
	v_exp_f32_e32 v164, v164
	v_exp_f32_e32 v165, v165
	v_exp_f32_e32 v166, v166
	v_exp_f32_e32 v167, v167
	v_exp_f32_e32 v168, v168
	v_exp_f32_e32 v169, v169
	v_exp_f32_e32 v170, v170
	v_exp_f32_e32 v171, v171
	v_exp_f32_e32 v172, v172
	v_exp_f32_e32 v173, v173
	v_exp_f32_e32 v174, v174
	v_exp_f32_e32 v175, v175
	v_exp_f32_e32 v176, v176
	v_exp_f32_e32 v177, v177
	v_exp_f32_e32 v178, v178
	v_exp_f32_e32 v179, v179
	v_exp_f32_e32 v180, v180
	v_exp_f32_e32 v181, v181
	v_exp_f32_e32 v182, v182
	v_exp_f32_e32 v183, v183
	v_exp_f32_e32 v184, v184
	v_exp_f32_e32 v185, v185
	v_exp_f32_e32 v186, v186
	v_exp_f32_e32 v187, v187
	v_exp_f32_e32 v188, v188
	v_exp_f32_e32 v189, v189
	v_exp_f32_e32 v190, v190
	v_exp_f32_e32 v191, v191
	v_exp_f32_e32 v192, v192
	v_exp_f32_e32 v193, v193
	v_add_f32_e32 v240, v162, v163
	v_add_f32_e32 v240, v240, v164
	v_add_f32_e32 v240, v240, v165
	v_add_f32_e32 v240, v240, v166
	v_add_f32_e32 v240, v240, v167
	v_add_f32_e32 v240, v240, v168
	v_add_f32_e32 v240, v240, v169
	v_add_f32_e32 v240, v240, v170
	v_add_f32_e32 v240, v240, v171
	v_add_f32_e32 v240, v240, v172
	v_add_f32_e32 v240, v240, v173
	v_add_f32_e32 v240, v240, v174
	v_add_f32_e32 v240, v240, v175
	v_add_f32_e32 v240, v240, v176
	v_add_f32_e32 v240, v240, v177
	v_add_f32_e32 v240, v240, v178
	v_add_f32_e32 v240, v240, v179
	v_add_f32_e32 v240, v240, v180
	v_add_f32_e32 v240, v240, v181
	v_add_f32_e32 v240, v240, v182
	v_add_f32_e32 v240, v240, v183
	v_add_f32_e32 v240, v240, v184
	v_add_f32_e32 v240, v240, v185
	v_add_f32_e32 v240, v240, v186
	v_add_f32_e32 v240, v240, v187
	v_add_f32_e32 v240, v240, v188
	v_add_f32_e32 v240, v240, v189
	v_add_f32_e32 v240, v240, v190
	v_add_f32_e32 v240, v240, v191
	v_add_f32_e32 v240, v240, v192
	v_add_f32_e32 v240, v240, v193
	v_mov_b32_e32 v241, v240
	v_cvt_pk_bf16_f32 v162, v162, v163
	v_cvt_pk_bf16_f32 v163, v164, v165
	v_cvt_pk_bf16_f32 v164, v166, v167
	v_cvt_pk_bf16_f32 v165, v168, v169
	v_cvt_pk_bf16_f32 v166, v170, v171
	v_cvt_pk_bf16_f32 v167, v172, v173
	v_cvt_pk_bf16_f32 v168, v174, v175
	v_cvt_pk_bf16_f32 v169, v176, v177
	v_cvt_pk_bf16_f32 v178, v178, v179
	v_cvt_pk_bf16_f32 v179, v180, v181
	v_cvt_pk_bf16_f32 v180, v182, v183
	v_cvt_pk_bf16_f32 v181, v184, v185
	v_cvt_pk_bf16_f32 v182, v186, v187
	v_cvt_pk_bf16_f32 v183, v188, v189
	v_cvt_pk_bf16_f32 v184, v190, v191
	v_cvt_pk_bf16_f32 v185, v192, v193
	s_nop 1
	v_permlane32_swap_b32_e32 v240, v241
	v_permlane32_swap_b32_e32 v162, v164
	v_permlane32_swap_b32_e32 v163, v165
	v_permlane32_swap_b32_e32 v166, v168
	v_permlane32_swap_b32_e32 v167, v169
	v_permlane32_swap_b32_e32 v178, v180
	v_permlane32_swap_b32_e32 v179, v181
	v_permlane32_swap_b32_e32 v182, v184
	v_permlane32_swap_b32_e32 v183, v185
	v_add_f32_e32 v240, v240, v241
	v_add_f32_e32 v239, v239, v240
	s_waitcnt vmcnt(0)
	s_barrier
	ds_read_b64_tr_b16 v[212:213], v236 offset:0
	ds_read_b64_tr_b16 v[214:215], v236 offset:4096
	ds_read_b64_tr_b16 v[216:217], v236 offset:8192
	ds_read_b64_tr_b16 v[218:219], v236 offset:12288
	ds_read_b64_tr_b16 v[220:221], v236 offset:16384
	ds_read_b64_tr_b16 v[222:223], v236 offset:20480
	ds_read_b64_tr_b16 v[224:225], v236 offset:24576
	ds_read_b64_tr_b16 v[226:227], v236 offset:28672
	ds_read_b64_tr_b16 v[170:171], v236 offset:512
	ds_read_b64_tr_b16 v[172:173], v236 offset:4608
	ds_read_b64_tr_b16 v[174:175], v236 offset:8704
	ds_read_b64_tr_b16 v[176:177], v236 offset:12800
	ds_read_b64_tr_b16 v[186:187], v236 offset:16896
	ds_read_b64_tr_b16 v[188:189], v236 offset:20992
	ds_read_b64_tr_b16 v[190:191], v236 offset:25088
	ds_read_b64_tr_b16 v[192:193], v236 offset:29184
	s_cmp_lt_u32 s13, 2
	s_cbranch_scc1 .Lap_nod_A0
	s_add_i32 m0, s47, 0xc000
	s_nop 0
	global_load_lds_dwordx4 v246, s[20:21]
	s_add_i32 m0, s47, 0xc400
	s_nop 0
	global_load_lds_dwordx4 v247, s[20:21]
	s_add_i32 m0, s47, 0xc800
	s_nop 0
	global_load_lds_dwordx4 v248, s[20:21]
	s_add_i32 m0, s47, 0xcc00
	s_nop 0
	global_load_lds_dwordx4 v249, s[20:21]
	s_add_u32 s20, s20, 0x40000
	s_addc_u32 s21, s21, 0
	s_cmp_lt_u32 s13, 3
	s_cbranch_scc1 .Lap_nod_A0
	s_add_i32 m0, s39, 0x0
	s_nop 0
	global_load_lds_dwordx4 v244, s[18:19]
	s_add_i32 m0, s39, 0x400
	s_nop 0
	global_load_lds_dwordx4 v245, s[18:19]
	s_add_u32 s18, s18, 0x40000
	s_addc_u32 s19, s19, 0
.Lap_nod_A0:
	s_waitcnt lgkmcnt(8)
	v_mfma_f32_32x32x16_bf16 v[0:15], v[162:165], v[212:215], v[0:15]
	v_mfma_f32_32x32x16_bf16 v[0:15], v[166:169], v[216:219], v[0:15]
	v_mfma_f32_32x32x16_bf16 v[0:15], v[178:181], v[220:223], v[0:15]
	v_mfma_f32_32x32x16_bf16 v[0:15], v[182:185], v[224:227], v[0:15]
	ds_read_b64_tr_b16 v[212:213], v236 offset:1024
	ds_read_b64_tr_b16 v[214:215], v236 offset:5120
	ds_read_b64_tr_b16 v[216:217], v236 offset:9216
	ds_read_b64_tr_b16 v[218:219], v236 offset:13312
	ds_read_b64_tr_b16 v[220:221], v236 offset:17408
	ds_read_b64_tr_b16 v[222:223], v236 offset:21504
	ds_read_b64_tr_b16 v[224:225], v236 offset:25600
	ds_read_b64_tr_b16 v[226:227], v236 offset:29696
	s_waitcnt lgkmcnt(8)
	v_mfma_f32_32x32x16_bf16 v[16:31], v[162:165], v[170:173], v[16:31]
	v_mfma_f32_32x32x16_bf16 v[16:31], v[166:169], v[174:177], v[16:31]
	v_mfma_f32_32x32x16_bf16 v[16:31], v[178:181], v[186:189], v[16:31]
	v_mfma_f32_32x32x16_bf16 v[16:31], v[182:185], v[190:193], v[16:31]
	ds_read_b64_tr_b16 v[170:171], v236 offset:1536
	ds_read_b64_tr_b16 v[172:173], v236 offset:5632
	ds_read_b64_tr_b16 v[174:175], v236 offset:9728
	ds_read_b64_tr_b16 v[176:177], v236 offset:13824
	ds_read_b64_tr_b16 v[186:187], v236 offset:17920
	ds_read_b64_tr_b16 v[188:189], v236 offset:22016
	ds_read_b64_tr_b16 v[190:191], v236 offset:26112
	ds_read_b64_tr_b16 v[192:193], v236 offset:30208
	s_waitcnt lgkmcnt(8)
	v_mfma_f32_32x32x16_bf16 v[32:47], v[162:165], v[212:215], v[32:47]
	v_mfma_f32_32x32x16_bf16 v[32:47], v[166:169], v[216:219], v[32:47]
	v_mfma_f32_32x32x16_bf16 v[32:47], v[178:181], v[220:223], v[32:47]
	v_mfma_f32_32x32x16_bf16 v[32:47], v[182:185], v[224:227], v[32:47]
	ds_read_b64_tr_b16 v[212:213], v236 offset:2048
	ds_read_b64_tr_b16 v[214:215], v236 offset:6144
	ds_read_b64_tr_b16 v[216:217], v236 offset:10240
	ds_read_b64_tr_b16 v[218:219], v236 offset:14336
	ds_read_b64_tr_b16 v[220:221], v236 offset:18432
	ds_read_b64_tr_b16 v[222:223], v236 offset:22528
	ds_read_b64_tr_b16 v[224:225], v236 offset:26624
	ds_read_b64_tr_b16 v[226:227], v236 offset:30720
	s_waitcnt lgkmcnt(8)
	v_mfma_f32_32x32x16_bf16 v[48:63], v[162:165], v[170:173], v[48:63]
	v_mfma_f32_32x32x16_bf16 v[48:63], v[166:169], v[174:177], v[48:63]
	v_mfma_f32_32x32x16_bf16 v[48:63], v[178:181], v[186:189], v[48:63]
	v_mfma_f32_32x32x16_bf16 v[48:63], v[182:185], v[190:193], v[48:63]
	ds_read_b64_tr_b16 v[170:171], v236 offset:2560
	ds_read_b64_tr_b16 v[172:173], v236 offset:6656
	ds_read_b64_tr_b16 v[174:175], v236 offset:10752
	ds_read_b64_tr_b16 v[176:177], v236 offset:14848
	ds_read_b64_tr_b16 v[186:187], v236 offset:18944
	ds_read_b64_tr_b16 v[188:189], v236 offset:23040
	ds_read_b64_tr_b16 v[190:191], v236 offset:27136
	ds_read_b64_tr_b16 v[192:193], v236 offset:31232
	s_waitcnt lgkmcnt(8)
	v_mfma_f32_32x32x16_bf16 v[64:79], v[162:165], v[212:215], v[64:79]
	v_mfma_f32_32x32x16_bf16 v[64:79], v[166:169], v[216:219], v[64:79]
	v_mfma_f32_32x32x16_bf16 v[64:79], v[178:181], v[220:223], v[64:79]
	v_mfma_f32_32x32x16_bf16 v[64:79], v[182:185], v[224:227], v[64:79]
	ds_read_b64_tr_b16 v[212:213], v236 offset:3072
	ds_read_b64_tr_b16 v[214:215], v236 offset:7168
	ds_read_b64_tr_b16 v[216:217], v236 offset:11264
	ds_read_b64_tr_b16 v[218:219], v236 offset:15360
	ds_read_b64_tr_b16 v[220:221], v236 offset:19456
	ds_read_b64_tr_b16 v[222:223], v236 offset:23552
	ds_read_b64_tr_b16 v[224:225], v236 offset:27648
	ds_read_b64_tr_b16 v[226:227], v236 offset:31744
	s_waitcnt lgkmcnt(8)
	v_mfma_f32_32x32x16_bf16 v[80:95], v[162:165], v[170:173], v[80:95]
	v_mfma_f32_32x32x16_bf16 v[80:95], v[166:169], v[174:177], v[80:95]
	v_mfma_f32_32x32x16_bf16 v[80:95], v[178:181], v[186:189], v[80:95]
	v_mfma_f32_32x32x16_bf16 v[80:95], v[182:185], v[190:193], v[80:95]
	ds_read_b64_tr_b16 v[170:171], v236 offset:3584
	ds_read_b64_tr_b16 v[172:173], v236 offset:7680
	ds_read_b64_tr_b16 v[174:175], v236 offset:11776
	ds_read_b64_tr_b16 v[176:177], v236 offset:15872
	ds_read_b64_tr_b16 v[186:187], v236 offset:19968
	ds_read_b64_tr_b16 v[188:189], v236 offset:24064
	ds_read_b64_tr_b16 v[190:191], v236 offset:28160
	ds_read_b64_tr_b16 v[192:193], v236 offset:32256
	s_waitcnt lgkmcnt(8)
	v_mfma_f32_32x32x16_bf16 v[98:113], v[162:165], v[212:215], v[98:113]
	v_mfma_f32_32x32x16_bf16 v[98:113], v[166:169], v[216:219], v[98:113]
	v_mfma_f32_32x32x16_bf16 v[98:113], v[178:181], v[220:223], v[98:113]
	v_mfma_f32_32x32x16_bf16 v[98:113], v[182:185], v[224:227], v[98:113]
	ds_read_b128 v[212:215], v228 offset:49152
	ds_read_b128 v[216:219], v228 offset:57344
	ds_read_b128 v[220:223], v229 offset:49152
	ds_read_b128 v[224:227], v229 offset:57344
	s_waitcnt lgkmcnt(4)
	v_mfma_f32_32x32x16_bf16 v[114:129], v[162:165], v[170:173], v[114:129]
	v_mfma_f32_32x32x16_bf16 v[114:129], v[166:169], v[174:177], v[114:129]
	v_mfma_f32_32x32x16_bf16 v[114:129], v[178:181], v[186:189], v[114:129]
	v_mfma_f32_32x32x16_bf16 v[114:129], v[182:185], v[190:193], v[114:129]
	s_cmp_lt_u32 s13, 2
	s_cbranch_scc1 .Lap_noqk_A0
	s_waitcnt lgkmcnt(2)
	v_mfma_f32_32x32x16_bf16 v[162:177], v[212:215], v[130:133], 0
	v_mfma_f32_32x32x16_bf16 v[178:193], v[216:219], v[130:133], 0
	ds_read_b128 v[212:215], v230 offset:49152
	ds_read_b128 v[216:219], v230 offset:57344
	s_waitcnt lgkmcnt(2)
	v_mfma_f32_32x32x16_bf16 v[162:177], v[220:223], v[134:137], v[162:177]
	v_mfma_f32_32x32x16_bf16 v[178:193], v[224:227], v[134:137], v[178:193]
	ds_read_b128 v[220:223], v231 offset:49152
	ds_read_b128 v[224:227], v231 offset:57344
	s_waitcnt lgkmcnt(2)
	v_mfma_f32_32x32x16_bf16 v[162:177], v[212:215], v[138:141], v[162:177]
	v_mfma_f32_32x32x16_bf16 v[178:193], v[216:219], v[138:141], v[178:193]
	ds_read_b128 v[212:215], v232 offset:49152
	ds_read_b128 v[216:219], v232 offset:57344
	s_waitcnt lgkmcnt(2)
	v_mfma_f32_32x32x16_bf16 v[162:177], v[220:223], v[142:145], v[162:177]
	v_mfma_f32_32x32x16_bf16 v[178:193], v[224:227], v[142:145], v[178:193]
	ds_read_b128 v[220:223], v233 offset:49152
	ds_read_b128 v[224:227], v233 offset:57344
	s_waitcnt lgkmcnt(2)
	v_mfma_f32_32x32x16_bf16 v[162:177], v[212:215], v[146:149], v[162:177]
	v_mfma_f32_32x32x16_bf16 v[178:193], v[216:219], v[146:149], v[178:193]
	ds_read_b128 v[212:215], v234 offset:49152
	ds_read_b128 v[216:219], v234 offset:57344
	s_waitcnt lgkmcnt(2)
	v_mfma_f32_32x32x16_bf16 v[162:177], v[220:223], v[150:153], v[162:177]
	v_mfma_f32_32x32x16_bf16 v[178:193], v[224:227], v[150:153], v[178:193]
	ds_read_b128 v[220:223], v235 offset:49152
	ds_read_b128 v[224:227], v235 offset:57344
	s_waitcnt lgkmcnt(2)
	v_mfma_f32_32x32x16_bf16 v[162:177], v[212:215], v[154:157], v[162:177]
	v_mfma_f32_32x32x16_bf16 v[178:193], v[216:219], v[154:157], v[178:193]
	s_waitcnt lgkmcnt(0)
	v_mfma_f32_32x32x16_bf16 v[162:177], v[220:223], v[158:161], v[162:177]
	v_mfma_f32_32x32x16_bf16 v[178:193], v[224:227], v[158:161], v[178:193]
.Lap_noqk_A0:
	s_waitcnt lgkmcnt(0)
	s_nop 7
	s_nop 4
	s_barrier
	s_sub_i32 s13, s13, 1
	v_max_f32_e32 v240, v162, v163
	v_max3_f32 v240, v240, v164, v165
	v_max3_f32 v240, v240, v166, v167
	v_max3_f32 v240, v240, v168, v169
	v_max3_f32 v240, v240, v170, v171
	v_max3_f32 v240, v240, v172, v173
	v_max3_f32 v240, v240, v174, v175
	v_max3_f32 v240, v240, v176, v177
	v_max3_f32 v240, v240, v178, v179
	v_max3_f32 v240, v240, v180, v181
	v_max3_f32 v240, v240, v182, v183
	v_max3_f32 v240, v240, v184, v185
	v_max3_f32 v240, v240, v186, v187
	v_max3_f32 v240, v240, v188, v189
	v_max3_f32 v240, v240, v190, v191
	v_max3_f32 v240, v240, v192, v193
	v_mov_b32_e32 v241, v240
	s_nop 1
	v_permlane32_swap_b32_e32 v240, v241
	v_max_f32_e32 v240, v240, v241
	v_sub_f32_e32 v241, v240, v238
	v_cmp_ge_f32_e32 vcc, 0x42b504f3, v241
	s_nop 3
	s_cmp_eq_u64 vcc, exec
	s_cbranch_scc1 .Lap_keep_A1
	v_max_f32_e32 v240, v238, v240
	v_sub_f32_e32 v241, v238, v240
	v_mul_f32_e32 v241, 0x3e0293ee, v241
	v_exp_f32_e32 v242, v241
	v_mov_b32_e32 v238, v240
	v_and_b32_e32 v240, 31, v96
	v_lshl_add_u32 v240, v240, 2, s50
	v_mul_f32_e32 v239, v239, v242
	ds_write_b32 v240, v242
	v_lshrrev_b32_e32 v240, 5, v96
	v_lshl_add_u32 v240, v240, 4, s50
	s_waitcnt lgkmcnt(0)
	ds_read_b128 v[212:215], v240 offset:0
	ds_read_b128 v[216:219], v240 offset:32
	ds_read_b128 v[220:223], v240 offset:64
	ds_read_b128 v[224:227], v240 offset:96
	s_waitcnt lgkmcnt(0)
	v_pk_mul_f32 v[0:1], v[0:1], v[212:213]
	v_pk_mul_f32 v[2:3], v[2:3], v[214:215]
	v_pk_mul_f32 v[4:5], v[4:5], v[216:217]
	v_pk_mul_f32 v[6:7], v[6:7], v[218:219]
	v_pk_mul_f32 v[8:9], v[8:9], v[220:221]
	v_pk_mul_f32 v[10:11], v[10:11], v[222:223]
	v_pk_mul_f32 v[12:13], v[12:13], v[224:225]
	v_pk_mul_f32 v[14:15], v[14:15], v[226:227]
	v_pk_mul_f32 v[16:17], v[16:17], v[212:213]
	v_pk_mul_f32 v[18:19], v[18:19], v[214:215]
	v_pk_mul_f32 v[20:21], v[20:21], v[216:217]
	v_pk_mul_f32 v[22:23], v[22:23], v[218:219]
	v_pk_mul_f32 v[24:25], v[24:25], v[220:221]
	v_pk_mul_f32 v[26:27], v[26:27], v[222:223]
	v_pk_mul_f32 v[28:29], v[28:29], v[224:225]
	v_pk_mul_f32 v[30:31], v[30:31], v[226:227]
	v_pk_mul_f32 v[32:33], v[32:33], v[212:213]
	v_pk_mul_f32 v[34:35], v[34:35], v[214:215]
	v_pk_mul_f32 v[36:37], v[36:37], v[216:217]
	v_pk_mul_f32 v[38:39], v[38:39], v[218:219]
	v_pk_mul_f32 v[40:41], v[40:41], v[220:221]
	v_pk_mul_f32 v[42:43], v[42:43], v[222:223]
	v_pk_mul_f32 v[44:45], v[44:45], v[224:225]
	v_pk_mul_f32 v[46:47], v[46:47], v[226:227]
	v_pk_mul_f32 v[48:49], v[48:49], v[212:213]
	v_pk_mul_f32 v[50:51], v[50:51], v[214:215]
	v_pk_mul_f32 v[52:53], v[52:53], v[216:217]
	v_pk_mul_f32 v[54:55], v[54:55], v[218:219]
	v_pk_mul_f32 v[56:57], v[56:57], v[220:221]
	v_pk_mul_f32 v[58:59], v[58:59], v[222:223]
	v_pk_mul_f32 v[60:61], v[60:61], v[224:225]
	v_pk_mul_f32 v[62:63], v[62:63], v[226:227]
	v_pk_mul_f32 v[64:65], v[64:65], v[212:213]
	v_pk_mul_f32 v[66:67], v[66:67], v[214:215]
	v_pk_mul_f32 v[68:69], v[68:69], v[216:217]
	v_pk_mul_f32 v[70:71], v[70:71], v[218:219]
	v_pk_mul_f32 v[72:73], v[72:73], v[220:221]
	v_pk_mul_f32 v[74:75], v[74:75], v[222:223]
	v_pk_mul_f32 v[76:77], v[76:77], v[224:225]
	v_pk_mul_f32 v[78:79], v[78:79], v[226:227]
	v_pk_mul_f32 v[80:81], v[80:81], v[212:213]
	v_pk_mul_f32 v[82:83], v[82:83], v[214:215]
	v_pk_mul_f32 v[84:85], v[84:85], v[216:217]
	v_pk_mul_f32 v[86:87], v[86:87], v[218:219]
	v_pk_mul_f32 v[88:89], v[88:89], v[220:221]
	v_pk_mul_f32 v[90:91], v[90:91], v[222:223]
	v_pk_mul_f32 v[92:93], v[92:93], v[224:225]
	v_pk_mul_f32 v[94:95], v[94:95], v[226:227]
	v_pk_mul_f32 v[98:99], v[98:99], v[212:213]
	v_pk_mul_f32 v[100:101], v[100:101], v[214:215]
	v_pk_mul_f32 v[102:103], v[102:103], v[216:217]
	v_pk_mul_f32 v[104:105], v[104:105], v[218:219]
	v_pk_mul_f32 v[106:107], v[106:107], v[220:221]
	v_pk_mul_f32 v[108:109], v[108:109], v[222:223]
	v_pk_mul_f32 v[110:111], v[110:111], v[224:225]
	v_pk_mul_f32 v[112:113], v[112:113], v[226:227]
	v_pk_mul_f32 v[114:115], v[114:115], v[212:213]
	v_pk_mul_f32 v[116:117], v[116:117], v[214:215]
	v_pk_mul_f32 v[118:119], v[118:119], v[216:217]
	v_pk_mul_f32 v[120:121], v[120:121], v[218:219]
	v_pk_mul_f32 v[122:123], v[122:123], v[220:221]
	v_pk_mul_f32 v[124:125], v[124:125], v[222:223]
	v_pk_mul_f32 v[126:127], v[126:127], v[224:225]
	v_pk_mul_f32 v[128:129], v[128:129], v[226:227]
.Lap_keep_A1:
	v_mul_f32_e32 v243, 0xbe0293ee, v238
	v_fmamk_f32 v162, v162, 0x3e0293ee, v243
	v_fmamk_f32 v163, v163, 0x3e0293ee, v243
	v_fmamk_f32 v164, v164, 0x3e0293ee, v243
	v_fmamk_f32 v165, v165, 0x3e0293ee, v243
	v_fmamk_f32 v166, v166, 0x3e0293ee, v243
	v_fmamk_f32 v167, v167, 0x3e0293ee, v243
	v_fmamk_f32 v168, v168, 0x3e0293ee, v243
	v_fmamk_f32 v169, v169, 0x3e0293ee, v243
	v_fmamk_f32 v170, v170, 0x3e0293ee, v243
	v_fmamk_f32 v171, v171, 0x3e0293ee, v243
	v_fmamk_f32 v172, v172, 0x3e0293ee, v243
	v_fmamk_f32 v173, v173, 0x3e0293ee, v243
	v_fmamk_f32 v174, v174, 0x3e0293ee, v243
	v_fmamk_f32 v175, v175, 0x3e0293ee, v243
	v_fmamk_f32 v176, v176, 0x3e0293ee, v243
	v_fmamk_f32 v177, v177, 0x3e0293ee, v243
	v_fmamk_f32 v178, v178, 0x3e0293ee, v243
	v_fmamk_f32 v179, v179, 0x3e0293ee, v243
	v_fmamk_f32 v180, v180, 0x3e0293ee, v243
	v_fmamk_f32 v181, v181, 0x3e0293ee, v243
	v_fmamk_f32 v182, v182, 0x3e0293ee, v243
	v_fmamk_f32 v183, v183, 0x3e0293ee, v243
	v_fmamk_f32 v184, v184, 0x3e0293ee, v243
	v_fmamk_f32 v185, v185, 0x3e0293ee, v243
	v_fmamk_f32 v186, v186, 0x3e0293ee, v243
	v_fmamk_f32 v187, v187, 0x3e0293ee, v243
	v_fmamk_f32 v188, v188, 0x3e0293ee, v243
	v_fmamk_f32 v189, v189, 0x3e0293ee, v243
	v_fmamk_f32 v190, v190, 0x3e0293ee, v243
	v_fmamk_f32 v191, v191, 0x3e0293ee, v243
	v_fmamk_f32 v192, v192, 0x3e0293ee, v243
	v_fmamk_f32 v193, v193, 0x3e0293ee, v243
	v_exp_f32_e32 v162, v162
	v_exp_f32_e32 v163, v163
	v_exp_f32_e32 v164, v164
	v_exp_f32_e32 v165, v165
	v_exp_f32_e32 v166, v166
	v_exp_f32_e32 v167, v167
	v_exp_f32_e32 v168, v168
	v_exp_f32_e32 v169, v169
	v_exp_f32_e32 v170, v170
	v_exp_f32_e32 v171, v171
	v_exp_f32_e32 v172, v172
	v_exp_f32_e32 v173, v173
	v_exp_f32_e32 v174, v174
	v_exp_f32_e32 v175, v175
	v_exp_f32_e32 v176, v176
	v_exp_f32_e32 v177, v177
	v_exp_f32_e32 v178, v178
	v_exp_f32_e32 v179, v179
	v_exp_f32_e32 v180, v180
	v_exp_f32_e32 v181, v181
	v_exp_f32_e32 v182, v182
	v_exp_f32_e32 v183, v183
	v_exp_f32_e32 v184, v184
	v_exp_f32_e32 v185, v185
	v_exp_f32_e32 v186, v186
	v_exp_f32_e32 v187, v187
	v_exp_f32_e32 v188, v188
	v_exp_f32_e32 v189, v189
	v_exp_f32_e32 v190, v190
	v_exp_f32_e32 v191, v191
	v_exp_f32_e32 v192, v192
	v_exp_f32_e32 v193, v193
	v_add_f32_e32 v240, v162, v163
	v_add_f32_e32 v240, v240, v164
	v_add_f32_e32 v240, v240, v165
	v_add_f32_e32 v240, v240, v166
	v_add_f32_e32 v240, v240, v167
	v_add_f32_e32 v240, v240, v168
	v_add_f32_e32 v240, v240, v169
	v_add_f32_e32 v240, v240, v170
	v_add_f32_e32 v240, v240, v171
	v_add_f32_e32 v240, v240, v172
	v_add_f32_e32 v240, v240, v173
	v_add_f32_e32 v240, v240, v174
	v_add_f32_e32 v240, v240, v175
	v_add_f32_e32 v240, v240, v176
	v_add_f32_e32 v240, v240, v177
	v_add_f32_e32 v240, v240, v178
	v_add_f32_e32 v240, v240, v179
	v_add_f32_e32 v240, v240, v180
	v_add_f32_e32 v240, v240, v181
	v_add_f32_e32 v240, v240, v182
	v_add_f32_e32 v240, v240, v183
	v_add_f32_e32 v240, v240, v184
	v_add_f32_e32 v240, v240, v185
	v_add_f32_e32 v240, v240, v186
	v_add_f32_e32 v240, v240, v187
	v_add_f32_e32 v240, v240, v188
	v_add_f32_e32 v240, v240, v189
	v_add_f32_e32 v240, v240, v190
	v_add_f32_e32 v240, v240, v191
	v_add_f32_e32 v240, v240, v192
	v_add_f32_e32 v240, v240, v193
	v_mov_b32_e32 v241, v240
	v_cvt_pk_bf16_f32 v162, v162, v163
	v_cvt_pk_bf16_f32 v163, v164, v165
	v_cvt_pk_bf16_f32 v164, v166, v167
	v_cvt_pk_bf16_f32 v165, v168, v169
	v_cvt_pk_bf16_f32 v166, v170, v171
	v_cvt_pk_bf16_f32 v167, v172, v173
	v_cvt_pk_bf16_f32 v168, v174, v175
	v_cvt_pk_bf16_f32 v169, v176, v177
	v_cvt_pk_bf16_f32 v178, v178, v179
	v_cvt_pk_bf16_f32 v179, v180, v181
	v_cvt_pk_bf16_f32 v180, v182, v183
	v_cvt_pk_bf16_f32 v181, v184, v185
	v_cvt_pk_bf16_f32 v182, v186, v187
	v_cvt_pk_bf16_f32 v183, v188, v189
	v_cvt_pk_bf16_f32 v184, v190, v191
	v_cvt_pk_bf16_f32 v185, v192, v193
	s_nop 1
	v_permlane32_swap_b32_e32 v240, v241
	v_permlane32_swap_b32_e32 v162, v164
	v_permlane32_swap_b32_e32 v163, v165
	v_permlane32_swap_b32_e32 v166, v168
	v_permlane32_swap_b32_e32 v167, v169
	v_permlane32_swap_b32_e32 v178, v180
	v_permlane32_swap_b32_e32 v179, v181
	v_permlane32_swap_b32_e32 v182, v184
	v_permlane32_swap_b32_e32 v183, v185
	v_add_f32_e32 v240, v240, v241
	v_add_f32_e32 v239, v239, v240
	s_waitcnt vmcnt(0)
	s_barrier
	ds_read_b64_tr_b16 v[212:213], v237 offset:0
	ds_read_b64_tr_b16 v[214:215], v237 offset:4096
	ds_read_b64_tr_b16 v[216:217], v237 offset:8192
	ds_read_b64_tr_b16 v[218:219], v237 offset:12288
	ds_read_b64_tr_b16 v[220:221], v237 offset:16384
	ds_read_b64_tr_b16 v[222:223], v237 offset:20480
	ds_read_b64_tr_b16 v[224:225], v237 offset:24576
	ds_read_b64_tr_b16 v[226:227], v237 offset:28672
	ds_read_b64_tr_b16 v[170:171], v237 offset:512
	ds_read_b64_tr_b16 v[172:173], v237 offset:4608
	ds_read_b64_tr_b16 v[174:175], v237 offset:8704
	ds_read_b64_tr_b16 v[176:177], v237 offset:12800
	ds_read_b64_tr_b16 v[186:187], v237 offset:16896
	ds_read_b64_tr_b16 v[188:189], v237 offset:20992
	ds_read_b64_tr_b16 v[190:191], v237 offset:25088
	ds_read_b64_tr_b16 v[192:193], v237 offset:29184
	s_cmp_lt_u32 s13, 2
	s_cbranch_scc1 .Lap_nod_A1
	s_add_i32 m0, s47, 0x0
	s_nop 0
	global_load_lds_dwordx4 v246, s[20:21]
	s_add_i32 m0, s47, 0x400
	s_nop 0
	global_load_lds_dwordx4 v247, s[20:21]
	s_add_i32 m0, s47, 0x800
	s_nop 0
	global_load_lds_dwordx4 v248, s[20:21]
	s_add_i32 m0, s47, 0xc00
	s_nop 0
	global_load_lds_dwordx4 v249, s[20:21]
	s_add_u32 s20, s20, 0x40000
	s_addc_u32 s21, s21, 0
	s_cmp_lt_u32 s13, 3
	s_cbranch_scc1 .Lap_nod_A1
	s_add_i32 m0, s39, 0xc000
	s_nop 0
	global_load_lds_dwordx4 v244, s[18:19]
	s_add_i32 m0, s39, 0xc400
	s_nop 0
	global_load_lds_dwordx4 v245, s[18:19]
	s_add_u32 s18, s18, 0x40000
	s_addc_u32 s19, s19, 0
.Lap_nod_A1:
	s_waitcnt lgkmcnt(8)
	v_mfma_f32_32x32x16_bf16 v[0:15], v[162:165], v[212:215], v[0:15]
	v_mfma_f32_32x32x16_bf16 v[0:15], v[166:169], v[216:219], v[0:15]
	v_mfma_f32_32x32x16_bf16 v[0:15], v[178:181], v[220:223], v[0:15]
	v_mfma_f32_32x32x16_bf16 v[0:15], v[182:185], v[224:227], v[0:15]
	ds_read_b64_tr_b16 v[212:213], v237 offset:1024
	ds_read_b64_tr_b16 v[214:215], v237 offset:5120
	ds_read_b64_tr_b16 v[216:217], v237 offset:9216
	ds_read_b64_tr_b16 v[218:219], v237 offset:13312
	ds_read_b64_tr_b16 v[220:221], v237 offset:17408
	ds_read_b64_tr_b16 v[222:223], v237 offset:21504
	ds_read_b64_tr_b16 v[224:225], v237 offset:25600
	ds_read_b64_tr_b16 v[226:227], v237 offset:29696
	s_waitcnt lgkmcnt(8)
	v_mfma_f32_32x32x16_bf16 v[16:31], v[162:165], v[170:173], v[16:31]
	v_mfma_f32_32x32x16_bf16 v[16:31], v[166:169], v[174:177], v[16:31]
	v_mfma_f32_32x32x16_bf16 v[16:31], v[178:181], v[186:189], v[16:31]
	v_mfma_f32_32x32x16_bf16 v[16:31], v[182:185], v[190:193], v[16:31]
	ds_read_b64_tr_b16 v[170:171], v237 offset:1536
	ds_read_b64_tr_b16 v[172:173], v237 offset:5632
	ds_read_b64_tr_b16 v[174:175], v237 offset:9728
	ds_read_b64_tr_b16 v[176:177], v237 offset:13824
	ds_read_b64_tr_b16 v[186:187], v237 offset:17920
	ds_read_b64_tr_b16 v[188:189], v237 offset:22016
	ds_read_b64_tr_b16 v[190:191], v237 offset:26112
	ds_read_b64_tr_b16 v[192:193], v237 offset:30208
	s_waitcnt lgkmcnt(8)
	v_mfma_f32_32x32x16_bf16 v[32:47], v[162:165], v[212:215], v[32:47]
	v_mfma_f32_32x32x16_bf16 v[32:47], v[166:169], v[216:219], v[32:47]
	v_mfma_f32_32x32x16_bf16 v[32:47], v[178:181], v[220:223], v[32:47]
	v_mfma_f32_32x32x16_bf16 v[32:47], v[182:185], v[224:227], v[32:47]
	ds_read_b64_tr_b16 v[212:213], v237 offset:2048
	ds_read_b64_tr_b16 v[214:215], v237 offset:6144
	ds_read_b64_tr_b16 v[216:217], v237 offset:10240
	ds_read_b64_tr_b16 v[218:219], v237 offset:14336
	ds_read_b64_tr_b16 v[220:221], v237 offset:18432
	ds_read_b64_tr_b16 v[222:223], v237 offset:22528
	ds_read_b64_tr_b16 v[224:225], v237 offset:26624
	ds_read_b64_tr_b16 v[226:227], v237 offset:30720
	s_waitcnt lgkmcnt(8)
	v_mfma_f32_32x32x16_bf16 v[48:63], v[162:165], v[170:173], v[48:63]
	v_mfma_f32_32x32x16_bf16 v[48:63], v[166:169], v[174:177], v[48:63]
	v_mfma_f32_32x32x16_bf16 v[48:63], v[178:181], v[186:189], v[48:63]
	v_mfma_f32_32x32x16_bf16 v[48:63], v[182:185], v[190:193], v[48:63]
	ds_read_b64_tr_b16 v[170:171], v237 offset:2560
	ds_read_b64_tr_b16 v[172:173], v237 offset:6656
	ds_read_b64_tr_b16 v[174:175], v237 offset:10752
	ds_read_b64_tr_b16 v[176:177], v237 offset:14848
	ds_read_b64_tr_b16 v[186:187], v237 offset:18944
	ds_read_b64_tr_b16 v[188:189], v237 offset:23040
	ds_read_b64_tr_b16 v[190:191], v237 offset:27136
	ds_read_b64_tr_b16 v[192:193], v237 offset:31232
	s_waitcnt lgkmcnt(8)
	v_mfma_f32_32x32x16_bf16 v[64:79], v[162:165], v[212:215], v[64:79]
	v_mfma_f32_32x32x16_bf16 v[64:79], v[166:169], v[216:219], v[64:79]
	v_mfma_f32_32x32x16_bf16 v[64:79], v[178:181], v[220:223], v[64:79]
	v_mfma_f32_32x32x16_bf16 v[64:79], v[182:185], v[224:227], v[64:79]
	ds_read_b64_tr_b16 v[212:213], v237 offset:3072
	ds_read_b64_tr_b16 v[214:215], v237 offset:7168
	ds_read_b64_tr_b16 v[216:217], v237 offset:11264
	ds_read_b64_tr_b16 v[218:219], v237 offset:15360
	ds_read_b64_tr_b16 v[220:221], v237 offset:19456
	ds_read_b64_tr_b16 v[222:223], v237 offset:23552
	ds_read_b64_tr_b16 v[224:225], v237 offset:27648
	ds_read_b64_tr_b16 v[226:227], v237 offset:31744
	s_waitcnt lgkmcnt(8)
	v_mfma_f32_32x32x16_bf16 v[80:95], v[162:165], v[170:173], v[80:95]
	v_mfma_f32_32x32x16_bf16 v[80:95], v[166:169], v[174:177], v[80:95]
	v_mfma_f32_32x32x16_bf16 v[80:95], v[178:181], v[186:189], v[80:95]
	v_mfma_f32_32x32x16_bf16 v[80:95], v[182:185], v[190:193], v[80:95]
	ds_read_b64_tr_b16 v[170:171], v237 offset:3584
	ds_read_b64_tr_b16 v[172:173], v237 offset:7680
	ds_read_b64_tr_b16 v[174:175], v237 offset:11776
	ds_read_b64_tr_b16 v[176:177], v237 offset:15872
	ds_read_b64_tr_b16 v[186:187], v237 offset:19968
	ds_read_b64_tr_b16 v[188:189], v237 offset:24064
	ds_read_b64_tr_b16 v[190:191], v237 offset:28160
	ds_read_b64_tr_b16 v[192:193], v237 offset:32256
	s_waitcnt lgkmcnt(8)
	v_mfma_f32_32x32x16_bf16 v[98:113], v[162:165], v[212:215], v[98:113]
	v_mfma_f32_32x32x16_bf16 v[98:113], v[166:169], v[216:219], v[98:113]
	v_mfma_f32_32x32x16_bf16 v[98:113], v[178:181], v[220:223], v[98:113]
	v_mfma_f32_32x32x16_bf16 v[98:113], v[182:185], v[224:227], v[98:113]
	ds_read_b128 v[212:215], v228 offset:0
	ds_read_b128 v[216:219], v228 offset:8192
	ds_read_b128 v[220:223], v229 offset:0
	ds_read_b128 v[224:227], v229 offset:8192
	s_waitcnt lgkmcnt(4)
	v_mfma_f32_32x32x16_bf16 v[114:129], v[162:165], v[170:173], v[114:129]
	v_mfma_f32_32x32x16_bf16 v[114:129], v[166:169], v[174:177], v[114:129]
	v_mfma_f32_32x32x16_bf16 v[114:129], v[178:181], v[186:189], v[114:129]
	v_mfma_f32_32x32x16_bf16 v[114:129], v[182:185], v[190:193], v[114:129]
	s_cmp_lt_u32 s13, 2
	s_cbranch_scc1 .Lap_noqk_A1
	s_waitcnt lgkmcnt(2)
	v_mfma_f32_32x32x16_bf16 v[162:177], v[212:215], v[130:133], 0
	v_mfma_f32_32x32x16_bf16 v[178:193], v[216:219], v[130:133], 0
	ds_read_b128 v[212:215], v230 offset:0
	ds_read_b128 v[216:219], v230 offset:8192
	s_waitcnt lgkmcnt(2)
	v_mfma_f32_32x32x16_bf16 v[162:177], v[220:223], v[134:137], v[162:177]
	v_mfma_f32_32x32x16_bf16 v[178:193], v[224:227], v[134:137], v[178:193]
	ds_read_b128 v[220:223], v231 offset:0
	ds_read_b128 v[224:227], v231 offset:8192
	s_waitcnt lgkmcnt(2)
	v_mfma_f32_32x32x16_bf16 v[162:177], v[212:215], v[138:141], v[162:177]
	v_mfma_f32_32x32x16_bf16 v[178:193], v[216:219], v[138:141], v[178:193]
	ds_read_b128 v[212:215], v232 offset:0
	ds_read_b128 v[216:219], v232 offset:8192
	s_waitcnt lgkmcnt(2)
	v_mfma_f32_32x32x16_bf16 v[162:177], v[220:223], v[142:145], v[162:177]
	v_mfma_f32_32x32x16_bf16 v[178:193], v[224:227], v[142:145], v[178:193]
	ds_read_b128 v[220:223], v233 offset:0
	ds_read_b128 v[224:227], v233 offset:8192
	s_waitcnt lgkmcnt(2)
	v_mfma_f32_32x32x16_bf16 v[162:177], v[212:215], v[146:149], v[162:177]
	v_mfma_f32_32x32x16_bf16 v[178:193], v[216:219], v[146:149], v[178:193]
	ds_read_b128 v[212:215], v234 offset:0
	ds_read_b128 v[216:219], v234 offset:8192
	s_waitcnt lgkmcnt(2)
	v_mfma_f32_32x32x16_bf16 v[162:177], v[220:223], v[150:153], v[162:177]
	v_mfma_f32_32x32x16_bf16 v[178:193], v[224:227], v[150:153], v[178:193]
	ds_read_b128 v[220:223], v235 offset:0
	ds_read_b128 v[224:227], v235 offset:8192
	s_waitcnt lgkmcnt(2)
	v_mfma_f32_32x32x16_bf16 v[162:177], v[212:215], v[154:157], v[162:177]
	v_mfma_f32_32x32x16_bf16 v[178:193], v[216:219], v[154:157], v[178:193]
	s_waitcnt lgkmcnt(0)
	v_mfma_f32_32x32x16_bf16 v[162:177], v[220:223], v[158:161], v[162:177]
	v_mfma_f32_32x32x16_bf16 v[178:193], v[224:227], v[158:161], v[178:193]
.Lap_noqk_A1:
	s_waitcnt lgkmcnt(0)
	s_nop 7
	s_nop 4
	s_barrier
	s_sub_i32 s13, s13, 1
	s_cmp_gt_u32 s13, 0
	s_cbranch_scc1 .Lap_loopA
	s_branch .Lap_epi
.Lap_B:
	s_add_i32 m0, s47, 0x0
	s_nop 0
	global_load_lds_dwordx4 v246, s[20:21]
	s_add_i32 m0, s47, 0x400
	s_nop 0
	global_load_lds_dwordx4 v247, s[20:21]
	s_add_i32 m0, s47, 0x800
	s_nop 0
	global_load_lds_dwordx4 v248, s[20:21]
	s_add_i32 m0, s47, 0xc00
	s_nop 0
	global_load_lds_dwordx4 v249, s[20:21]
	s_add_u32 s20, s20, 0x40000
	s_addc_u32 s21, s21, 0
	s_add_i32 m0, s39, 0xc000
	s_nop 0
	global_load_lds_dwordx4 v244, s[18:19]
	s_add_i32 m0, s39, 0xc400
	s_nop 0
	global_load_lds_dwordx4 v245, s[18:19]
	s_add_u32 s18, s18, 0x40000
	s_addc_u32 s19, s19, 0
	s_barrier
	ds_read_b128 v[212:215], v228 offset:0
	ds_read_b128 v[216:219], v228 offset:8192
	ds_read_b128 v[220:223], v229 offset:0
	ds_read_b128 v[224:227], v229 offset:8192
	s_waitcnt lgkmcnt(2)
	v_mfma_f32_32x32x16_bf16 v[162:177], v[212:215], v[130:133], 0
	v_mfma_f32_32x32x16_bf16 v[178:193], v[216:219], v[130:133], 0
	ds_read_b128 v[212:215], v230 offset:0
	ds_read_b128 v[216:219], v230 offset:8192
	s_waitcnt lgkmcnt(2)
	v_mfma_f32_32x32x16_bf16 v[162:177], v[220:223], v[134:137], v[162:177]
	v_mfma_f32_32x32x16_bf16 v[178:193], v[224:227], v[134:137], v[178:193]
	ds_read_b128 v[220:223], v231 offset:0
	ds_read_b128 v[224:227], v231 offset:8192
	s_waitcnt lgkmcnt(2)
	v_mfma_f32_32x32x16_bf16 v[162:177], v[212:215], v[138:141], v[162:177]
	v_mfma_f32_32x32x16_bf16 v[178:193], v[216:219], v[138:141], v[178:193]
	ds_read_b128 v[212:215], v232 offset:0
	ds_read_b128 v[216:219], v232 offset:8192
	s_waitcnt lgkmcnt(2)
	v_mfma_f32_32x32x16_bf16 v[162:177], v[220:223], v[142:145], v[162:177]
	v_mfma_f32_32x32x16_bf16 v[178:193], v[224:227], v[142:145], v[178:193]
	ds_read_b128 v[220:223], v233 offset:0
	ds_read_b128 v[224:227], v233 offset:8192
	s_waitcnt lgkmcnt(2)
	v_mfma_f32_32x32x16_bf16 v[162:177], v[212:215], v[146:149], v[162:177]
	v_mfma_f32_32x32x16_bf16 v[178:193], v[216:219], v[146:149], v[178:193]
	ds_read_b128 v[212:215], v234 offset:0
	ds_read_b128 v[216:219], v234 offset:8192
	s_waitcnt lgkmcnt(2)
	v_mfma_f32_32x32x16_bf16 v[162:177], v[220:223], v[150:153], v[162:177]
	v_mfma_f32_32x32x16_bf16 v[178:193], v[224:227], v[150:153], v[178:193]
	ds_read_b128 v[220:223], v235 offset:0
	ds_read_b128 v[224:227], v235 offset:8192
	s_waitcnt lgkmcnt(2)
	v_mfma_f32_32x32x16_bf16 v[162:177], v[212:215], v[154:157], v[162:177]
	v_mfma_f32_32x32x16_bf16 v[178:193], v[216:219], v[154:157], v[178:193]
	s_waitcnt lgkmcnt(0)
	v_mfma_f32_32x32x16_bf16 v[162:177], v[220:223], v[158:161], v[162:177]
	v_mfma_f32_32x32x16_bf16 v[178:193], v[224:227], v[158:161], v[178:193]
	s_nop 7
	s_nop 4
	s_waitcnt vmcnt(0)
	s_barrier
.Lap_loopB:
	s_cmp_lt_u32 s13, 2
	s_cbranch_scc1 .Lap_nod_B0
	s_add_i32 m0, s47, 0xc000
	s_nop 0
	global_load_lds_dwordx4 v246, s[20:21]
	s_add_i32 m0, s47, 0xc400
	s_nop 0
	global_load_lds_dwordx4 v247, s[20:21]
	s_add_i32 m0, s47, 0xc800
	s_nop 0
	global_load_lds_dwordx4 v248, s[20:21]
	s_add_i32 m0, s47, 0xcc00
	s_nop 0
	global_load_lds_dwordx4 v249, s[20:21]
	s_add_u32 s20, s20, 0x40000
	s_addc_u32 s21, s21, 0
	s_cmp_lt_u32 s13, 3
	s_cbranch_scc1 .Lap_nod_B0
	s_add_i32 m0, s39, 0x0
	s_nop 0
	global_load_lds_dwordx4 v244, s[18:19]
	s_add_i32 m0, s39, 0x400
	s_nop 0
	global_load_lds_dwordx4 v245, s[18:19]
	s_add_u32 s18, s18, 0x40000
	s_addc_u32 s19, s19, 0

.Lap_keep_B0:
	v_mul_f32_e32 v243, 0xbe0293ee, v238
	v_fmamk_f32 v162, v162, 0x3e0293ee, v243
	v_fmamk_f32 v163, v163, 0x3e0293ee, v243
	v_fmamk_f32 v164, v164, 0x3e0293ee, v243
	v_fmamk_f32 v165, v165, 0x3e0293ee, v243
	v_fmamk_f32 v166, v166, 0x3e0293ee, v243
	v_fmamk_f32 v167, v167, 0x3e0293ee, v243
	v_fmamk_f32 v168, v168, 0x3e0293ee, v243
	v_fmamk_f32 v169, v169, 0x3e0293ee, v243
	v_fmamk_f32 v170, v170, 0x3e0293ee, v243
	v_fmamk_f32 v171, v171, 0x3e0293ee, v243
	v_fmamk_f32 v172, v172, 0x3e0293ee, v243
	v_fmamk_f32 v173, v173, 0x3e0293ee, v243
	v_fmamk_f32 v174, v174, 0x3e0293ee, v243
	v_fmamk_f32 v175, v175, 0x3e0293ee, v243
	v_fmamk_f32 v176, v176, 0x3e0293ee, v243
	v_fmamk_f32 v177, v177, 0x3e0293ee, v243
	v_fmamk_f32 v178, v178, 0x3e0293ee, v243
	v_fmamk_f32 v179, v179, 0x3e0293ee, v243
	v_fmamk_f32 v180, v180, 0x3e0293ee, v243
	v_fmamk_f32 v181, v181, 0x3e0293ee, v243
	v_fmamk_f32 v182, v182, 0x3e0293ee, v243
	v_fmamk_f32 v183, v183, 0x3e0293ee, v243
	v_fmamk_f32 v184, v184, 0x3e0293ee, v243
	v_fmamk_f32 v185, v185, 0x3e0293ee, v243
	v_fmamk_f32 v186, v186, 0x3e0293ee, v243
	v_fmamk_f32 v187, v187, 0x3e0293ee, v243
	v_fmamk_f32 v188, v188, 0x3e0293ee, v243
	v_fmamk_f32 v189, v189, 0x3e0293ee, v243
	v_fmamk_f32 v190, v190, 0x3e0293ee, v243
	v_fmamk_f32 v191, v191, 0x3e0293ee, v243
	v_fmamk_f32 v192, v192, 0x3e0293ee, v243
	v_fmamk_f32 v193, v193, 0x3e0293ee, v243
	v_exp_f32_e32 v162, v162
	v_exp_f32_e32 v163, v163
	v_exp_f32_e32 v164, v164
	v_exp_f32_e32 v165, v165
	v_exp_f32_e32 v166, v166
	v_exp_f32_e32 v167, v167
	v_exp_f32_e32 v168, v168
	v_exp_f32_e32 v169, v169
	v_exp_f32_e32 v170, v170
	v_exp_f32_e32 v171, v171
	v_exp_f32_e32 v172, v172
	v_exp_f32_e32 v173, v173
	v_exp_f32_e32 v174, v174
	v_exp_f32_e32 v175, v175
	v_exp_f32_e32 v176, v176
	v_exp_f32_e32 v177, v177
	v_exp_f32_e32 v178, v178
	v_exp_f32_e32 v179, v179
	v_exp_f32_e32 v180, v180
	v_exp_f32_e32 v181, v181
	v_exp_f32_e32 v182, v182
	v_exp_f32_e32 v183, v183
	v_exp_f32_e32 v184, v184
	v_exp_f32_e32 v185, v185
	v_exp_f32_e32 v186, v186
	v_exp_f32_e32 v187, v187
	v_exp_f32_e32 v188, v188
	v_exp_f32_e32 v189, v189
	v_exp_f32_e32 v190, v190
	v_exp_f32_e32 v191, v191
	v_exp_f32_e32 v192, v192
	v_exp_f32_e32 v193, v193
	v_add_f32_e32 v240, v162, v163
	v_add_f32_e32 v240, v240, v164
	v_add_f32_e32 v240, v240, v165
	v_add_f32_e32 v240, v240, v166
	v_add_f32_e32 v240, v240, v167
	v_add_f32_e32 v240, v240, v168
	v_add_f32_e32 v240, v240, v169
	v_add_f32_e32 v240, v240, v170
	v_add_f32_e32 v240, v240, v171
	v_add_f32_e32 v240, v240, v172
	v_add_f32_e32 v240, v240, v173
	v_add_f32_e32 v240, v240, v174
	v_add_f32_e32 v240, v240, v175
	v_add_f32_e32 v240, v240, v176
	v_add_f32_e32 v240, v240, v177
	v_add_f32_e32 v240, v240, v178
	v_add_f32_e32 v240, v240, v179
	v_add_f32_e32 v240, v240, v180
	v_add_f32_e32 v240, v240, v181
	v_add_f32_e32 v240, v240, v182
	v_add_f32_e32 v240, v240, v183
	v_add_f32_e32 v240, v240, v184
	v_add_f32_e32 v240, v240, v185
	v_add_f32_e32 v240, v240, v186
	v_add_f32_e32 v240, v240, v187
	v_add_f32_e32 v240, v240, v188
	v_add_f32_e32 v240, v240, v189
	v_add_f32_e32 v240, v240, v190
	v_add_f32_e32 v240, v240, v191
	v_add_f32_e32 v240, v240, v192
	v_add_f32_e32 v240, v240, v193
	v_mov_b32_e32 v241, v240
	v_cvt_pk_bf16_f32 v162, v162, v163
	v_cvt_pk_bf16_f32 v163, v164, v165
	v_cvt_pk_bf16_f32 v164, v166, v167
	v_cvt_pk_bf16_f32 v165, v168, v169
	v_cvt_pk_bf16_f32 v166, v170, v171
	v_cvt_pk_bf16_f32 v167, v172, v173
	v_cvt_pk_bf16_f32 v168, v174, v175
	v_cvt_pk_bf16_f32 v169, v176, v177
	v_cvt_pk_bf16_f32 v178, v178, v179
	v_cvt_pk_bf16_f32 v179, v180, v181
	v_cvt_pk_bf16_f32 v180, v182, v183
	v_cvt_pk_bf16_f32 v181, v184, v185
	v_cvt_pk_bf16_f32 v182, v186, v187
	v_cvt_pk_bf16_f32 v183, v188, v189
	v_cvt_pk_bf16_f32 v184, v190, v191
	v_cvt_pk_bf16_f32 v185, v192, v193
	s_nop 1
	v_permlane32_swap_b32_e32 v240, v241
	v_permlane32_swap_b32_e32 v162, v164
	v_permlane32_swap_b32_e32 v163, v165
	v_permlane32_swap_b32_e32 v166, v168
	v_permlane32_swap_b32_e32 v167, v169
	v_permlane32_swap_b32_e32 v178, v180
	v_permlane32_swap_b32_e32 v179, v181
	v_permlane32_swap_b32_e32 v182, v184
	v_permlane32_swap_b32_e32 v183, v185
	v_add_f32_e32 v240, v240, v241
	v_add_f32_e32 v239, v239, v240
	s_barrier
	ds_read_b64_tr_b16 v[212:213], v236 offset:0
	ds_read_b64_tr_b16 v[214:215], v236 offset:4096
	ds_read_b64_tr_b16 v[216:217], v236 offset:8192
	ds_read_b64_tr_b16 v[218:219], v236 offset:12288
	ds_read_b64_tr_b16 v[220:221], v236 offset:16384
	ds_read_b64_tr_b16 v[222:223], v236 offset:20480
	ds_read_b64_tr_b16 v[224:225], v236 offset:24576
	ds_read_b64_tr_b16 v[226:227], v236 offset:28672
	ds_read_b64_tr_b16 v[170:171], v236 offset:512
	ds_read_b64_tr_b16 v[172:173], v236 offset:4608
	ds_read_b64_tr_b16 v[174:175], v236 offset:8704
	ds_read_b64_tr_b16 v[176:177], v236 offset:12800
	ds_read_b64_tr_b16 v[186:187], v236 offset:16896
	ds_read_b64_tr_b16 v[188:189], v236 offset:20992
	ds_read_b64_tr_b16 v[190:191], v236 offset:25088
	ds_read_b64_tr_b16 v[192:193], v236 offset:29184
	s_waitcnt lgkmcnt(8)
	v_mfma_f32_32x32x16_bf16 v[0:15], v[162:165], v[212:215], v[0:15]
	v_mfma_f32_32x32x16_bf16 v[0:15], v[166:169], v[216:219], v[0:15]
	v_mfma_f32_32x32x16_bf16 v[0:15], v[178:181], v[220:223], v[0:15]
	v_mfma_f32_32x32x16_bf16 v[0:15], v[182:185], v[224:227], v[0:15]
	ds_read_b64_tr_b16 v[212:213], v236 offset:1024
	ds_read_b64_tr_b16 v[214:215], v236 offset:5120
	ds_read_b64_tr_b16 v[216:217], v236 offset:9216
	ds_read_b64_tr_b16 v[218:219], v236 offset:13312
	ds_read_b64_tr_b16 v[220:221], v236 offset:17408
	ds_read_b64_tr_b16 v[222:223], v236 offset:21504
	ds_read_b64_tr_b16 v[224:225], v236 offset:25600
	ds_read_b64_tr_b16 v[226:227], v236 offset:29696
	s_waitcnt lgkmcnt(8)
	v_mfma_f32_32x32x16_bf16 v[16:31], v[162:165], v[170:173], v[16:31]
	v_mfma_f32_32x32x16_bf16 v[16:31], v[166:169], v[174:177], v[16:31]
	v_mfma_f32_32x32x16_bf16 v[16:31], v[178:181], v[186:189], v[16:31]
	v_mfma_f32_32x32x16_bf16 v[16:31], v[182:185], v[190:193], v[16:31]
	ds_read_b64_tr_b16 v[170:171], v236 offset:1536
	ds_read_b64_tr_b16 v[172:173], v236 offset:5632
	ds_read_b64_tr_b16 v[174:175], v236 offset:9728
	ds_read_b64_tr_b16 v[176:177], v236 offset:13824
	ds_read_b64_tr_b16 v[186:187], v236 offset:17920
	ds_read_b64_tr_b16 v[188:189], v236 offset:22016
	ds_read_b64_tr_b16 v[190:191], v236 offset:26112
	ds_read_b64_tr_b16 v[192:193], v236 offset:30208
	s_waitcnt lgkmcnt(8)
	v_mfma_f32_32x32x16_bf16 v[32:47], v[162:165], v[212:215], v[32:47]
	v_mfma_f32_32x32x16_bf16 v[32:47], v[166:169], v[216:219], v[32:47]
	v_mfma_f32_32x32x16_bf16 v[32:47], v[178:181], v[220:223], v[32:47]
	v_mfma_f32_32x32x16_bf16 v[32:47], v[182:185], v[224:227], v[32:47]
	ds_read_b64_tr_b16 v[212:213], v236 offset:2048
	ds_read_b64_tr_b16 v[214:215], v236 offset:6144
	ds_read_b64_tr_b16 v[216:217], v236 offset:10240
	ds_read_b64_tr_b16 v[218:219], v236 offset:14336
	ds_read_b64_tr_b16 v[220:221], v236 offset:18432
	ds_read_b64_tr_b16 v[222:223], v236 offset:22528
	ds_read_b64_tr_b16 v[224:225], v236 offset:26624
	ds_read_b64_tr_b16 v[226:227], v236 offset:30720
	s_waitcnt lgkmcnt(8)
	v_mfma_f32_32x32x16_bf16 v[48:63], v[162:165], v[170:173], v[48:63]
	v_mfma_f32_32x32x16_bf16 v[48:63], v[166:169], v[174:177], v[48:63]
	v_mfma_f32_32x32x16_bf16 v[48:63], v[178:181], v[186:189], v[48:63]
	v_mfma_f32_32x32x16_bf16 v[48:63], v[182:185], v[190:193], v[48:63]
	ds_read_b64_tr_b16 v[170:171], v236 offset:2560
	ds_read_b64_tr_b16 v[172:173], v236 offset:6656
	ds_read_b64_tr_b16 v[174:175], v236 offset:10752
	ds_read_b64_tr_b16 v[176:177], v236 offset:14848
	ds_read_b64_tr_b16 v[186:187], v236 offset:18944
	ds_read_b64_tr_b16 v[188:189], v236 offset:23040
	ds_read_b64_tr_b16 v[190:191], v236 offset:27136
	ds_read_b64_tr_b16 v[192:193], v236 offset:31232
	s_waitcnt lgkmcnt(8)
	v_mfma_f32_32x32x16_bf16 v[64:79], v[162:165], v[212:215], v[64:79]
	v_mfma_f32_32x32x16_bf16 v[64:79], v[166:169], v[216:219], v[64:79]
	v_mfma_f32_32x32x16_bf16 v[64:79], v[178:181], v[220:223], v[64:79]
	v_mfma_f32_32x32x16_bf16 v[64:79], v[182:185], v[224:227], v[64:79]
	ds_read_b64_tr_b16 v[212:213], v236 offset:3072
	ds_read_b64_tr_b16 v[214:215], v236 offset:7168
	ds_read_b64_tr_b16 v[216:217], v236 offset:11264
	ds_read_b64_tr_b16 v[218:219], v236 offset:15360
	ds_read_b64_tr_b16 v[220:221], v236 offset:19456
	ds_read_b64_tr_b16 v[222:223], v236 offset:23552
	ds_read_b64_tr_b16 v[224:225], v236 offset:27648
	ds_read_b64_tr_b16 v[226:227], v236 offset:31744
	s_waitcnt lgkmcnt(8)
	v_mfma_f32_32x32x16_bf16 v[80:95], v[162:165], v[170:173], v[80:95]
	v_mfma_f32_32x32x16_bf16 v[80:95], v[166:169], v[174:177], v[80:95]
	v_mfma_f32_32x32x16_bf16 v[80:95], v[178:181], v[186:189], v[80:95]
	v_mfma_f32_32x32x16_bf16 v[80:95], v[182:185], v[190:193], v[80:95]
	ds_read_b64_tr_b16 v[170:171], v236 offset:3584
	ds_read_b64_tr_b16 v[172:173], v236 offset:7680
	ds_read_b64_tr_b16 v[174:175], v236 offset:11776
	ds_read_b64_tr_b16 v[176:177], v236 offset:15872
	ds_read_b64_tr_b16 v[186:187], v236 offset:19968
	ds_read_b64_tr_b16 v[188:189], v236 offset:24064
	ds_read_b64_tr_b16 v[190:191], v236 offset:28160
	ds_read_b64_tr_b16 v[192:193], v236 offset:32256
	s_waitcnt lgkmcnt(8)
	v_mfma_f32_32x32x16_bf16 v[98:113], v[162:165], v[212:215], v[98:113]
	v_mfma_f32_32x32x16_bf16 v[98:113], v[166:169], v[216:219], v[98:113]
	v_mfma_f32_32x32x16_bf16 v[98:113], v[178:181], v[220:223], v[98:113]
	v_mfma_f32_32x32x16_bf16 v[98:113], v[182:185], v[224:227], v[98:113]
	ds_read_b128 v[212:215], v228 offset:49152
	ds_read_b128 v[216:219], v228 offset:57344
	ds_read_b128 v[220:223], v229 offset:49152
	ds_read_b128 v[224:227], v229 offset:57344
	s_waitcnt lgkmcnt(4)
	v_mfma_f32_32x32x16_bf16 v[114:129], v[162:165], v[170:173], v[114:129]
	v_mfma_f32_32x32x16_bf16 v[114:129], v[166:169], v[174:177], v[114:129]
	v_mfma_f32_32x32x16_bf16 v[114:129], v[178:181], v[186:189], v[114:129]
	v_mfma_f32_32x32x16_bf16 v[114:129], v[182:185], v[190:193], v[114:129]
	s_cmp_lt_u32 s13, 2
	s_cbranch_scc1 .Lap_noqk_B0
	s_waitcnt lgkmcnt(2)
	v_mfma_f32_32x32x16_bf16 v[162:177], v[212:215], v[130:133], 0
	v_mfma_f32_32x32x16_bf16 v[178:193], v[216:219], v[130:133], 0
	ds_read_b128 v[212:215], v230 offset:49152
	ds_read_b128 v[216:219], v230 offset:57344
	s_waitcnt lgkmcnt(2)
	v_mfma_f32_32x32x16_bf16 v[162:177], v[220:223], v[134:137], v[162:177]
	v_mfma_f32_32x32x16_bf16 v[178:193], v[224:227], v[134:137], v[178:193]
	ds_read_b128 v[220:223], v231 offset:49152
	ds_read_b128 v[224:227], v231 offset:57344
	s_waitcnt lgkmcnt(2)
	v_mfma_f32_32x32x16_bf16 v[162:177], v[212:215], v[138:141], v[162:177]
	v_mfma_f32_32x32x16_bf16 v[178:193], v[216:219], v[138:141], v[178:193]
	ds_read_b128 v[212:215], v232 offset:49152
	ds_read_b128 v[216:219], v232 offset:57344
	s_waitcnt lgkmcnt(2)
	v_mfma_f32_32x32x16_bf16 v[162:177], v[220:223], v[142:145], v[162:177]
	v_mfma_f32_32x32x16_bf16 v[178:193], v[224:227], v[142:145], v[178:193]
	ds_read_b128 v[220:223], v233 offset:49152
	ds_read_b128 v[224:227], v233 offset:57344
	s_waitcnt lgkmcnt(2)
	v_mfma_f32_32x32x16_bf16 v[162:177], v[212:215], v[146:149], v[162:177]
	v_mfma_f32_32x32x16_bf16 v[178:193], v[216:219], v[146:149], v[178:193]
	ds_read_b128 v[212:215], v234 offset:49152
	ds_read_b128 v[216:219], v234 offset:57344
	s_waitcnt lgkmcnt(2)
	v_mfma_f32_32x32x16_bf16 v[162:177], v[220:223], v[150:153], v[162:177]
	v_mfma_f32_32x32x16_bf16 v[178:193], v[224:227], v[150:153], v[178:193]
	ds_read_b128 v[220:223], v235 offset:49152
	ds_read_b128 v[224:227], v235 offset:57344
	s_waitcnt lgkmcnt(2)
	v_mfma_f32_32x32x16_bf16 v[162:177], v[212:215], v[154:157], v[162:177]
	v_mfma_f32_32x32x16_bf16 v[178:193], v[216:219], v[154:157], v[178:193]
	s_waitcnt lgkmcnt(0)
	v_mfma_f32_32x32x16_bf16 v[162:177], v[220:223], v[158:161], v[162:177]
	v_mfma_f32_32x32x16_bf16 v[178:193], v[224:227], v[158:161], v[178:193]
.Lap_noqk_B0:
	s_waitcnt lgkmcnt(0)
	s_nop 7
	s_nop 4
	s_waitcnt vmcnt(0)
	s_barrier
	s_sub_i32 s13, s13, 1
	s_cmp_lt_u32 s13, 2
	s_cbranch_scc1 .Lap_nod_B1
	s_add_i32 m0, s47, 0x0
	s_nop 0
	global_load_lds_dwordx4 v246, s[20:21]
	s_add_i32 m0, s47, 0x400
	s_nop 0
	global_load_lds_dwordx4 v247, s[20:21]
	s_add_i32 m0, s47, 0x800
	s_nop 0
	global_load_lds_dwordx4 v248, s[20:21]
	s_add_i32 m0, s47, 0xc00
	s_nop 0
	global_load_lds_dwordx4 v249, s[20:21]
	s_add_u32 s20, s20, 0x40000
	s_addc_u32 s21, s21, 0
	s_cmp_lt_u32 s13, 3
	s_cbranch_scc1 .Lap_nod_B1
	s_add_i32 m0, s39, 0xc000
	s_nop 0
	global_load_lds_dwordx4 v244, s[18:19]
	s_add_i32 m0, s39, 0xc400
	s_nop 0
	global_load_lds_dwordx4 v245, s[18:19]
	s_add_u32 s18, s18, 0x40000
	s_addc_u32 s19, s19, 0

.Lap_keep_B1:
	v_mul_f32_e32 v243, 0xbe0293ee, v238
	v_fmamk_f32 v162, v162, 0x3e0293ee, v243
	v_fmamk_f32 v163, v163, 0x3e0293ee, v243
	v_fmamk_f32 v164, v164, 0x3e0293ee, v243
	v_fmamk_f32 v165, v165, 0x3e0293ee, v243
	v_fmamk_f32 v166, v166, 0x3e0293ee, v243
	v_fmamk_f32 v167, v167, 0x3e0293ee, v243
	v_fmamk_f32 v168, v168, 0x3e0293ee, v243
	v_fmamk_f32 v169, v169, 0x3e0293ee, v243
	v_fmamk_f32 v170, v170, 0x3e0293ee, v243
	v_fmamk_f32 v171, v171, 0x3e0293ee, v243
	v_fmamk_f32 v172, v172, 0x3e0293ee, v243
	v_fmamk_f32 v173, v173, 0x3e0293ee, v243
	v_fmamk_f32 v174, v174, 0x3e0293ee, v243
	v_fmamk_f32 v175, v175, 0x3e0293ee, v243
	v_fmamk_f32 v176, v176, 0x3e0293ee, v243
	v_fmamk_f32 v177, v177, 0x3e0293ee, v243
	v_fmamk_f32 v178, v178, 0x3e0293ee, v243
	v_fmamk_f32 v179, v179, 0x3e0293ee, v243
	v_fmamk_f32 v180, v180, 0x3e0293ee, v243
	v_fmamk_f32 v181, v181, 0x3e0293ee, v243
	v_fmamk_f32 v182, v182, 0x3e0293ee, v243
	v_fmamk_f32 v183, v183, 0x3e0293ee, v243
	v_fmamk_f32 v184, v184, 0x3e0293ee, v243
	v_fmamk_f32 v185, v185, 0x3e0293ee, v243
	v_fmamk_f32 v186, v186, 0x3e0293ee, v243
	v_fmamk_f32 v187, v187, 0x3e0293ee, v243
	v_fmamk_f32 v188, v188, 0x3e0293ee, v243
	v_fmamk_f32 v189, v189, 0x3e0293ee, v243
	v_fmamk_f32 v190, v190, 0x3e0293ee, v243
	v_fmamk_f32 v191, v191, 0x3e0293ee, v243
	v_fmamk_f32 v192, v192, 0x3e0293ee, v243
	v_fmamk_f32 v193, v193, 0x3e0293ee, v243
	v_exp_f32_e32 v162, v162
	v_exp_f32_e32 v163, v163
	v_exp_f32_e32 v164, v164
	v_exp_f32_e32 v165, v165
	v_exp_f32_e32 v166, v166
	v_exp_f32_e32 v167, v167
	v_exp_f32_e32 v168, v168
	v_exp_f32_e32 v169, v169
	v_exp_f32_e32 v170, v170
	v_exp_f32_e32 v171, v171
	v_exp_f32_e32 v172, v172
	v_exp_f32_e32 v173, v173
	v_exp_f32_e32 v174, v174
	v_exp_f32_e32 v175, v175
	v_exp_f32_e32 v176, v176
	v_exp_f32_e32 v177, v177
	v_exp_f32_e32 v178, v178
	v_exp_f32_e32 v179, v179
	v_exp_f32_e32 v180, v180
	v_exp_f32_e32 v181, v181
	v_exp_f32_e32 v182, v182
	v_exp_f32_e32 v183, v183
	v_exp_f32_e32 v184, v184
	v_exp_f32_e32 v185, v185
	v_exp_f32_e32 v186, v186
	v_exp_f32_e32 v187, v187
	v_exp_f32_e32 v188, v188
	v_exp_f32_e32 v189, v189
	v_exp_f32_e32 v190, v190
	v_exp_f32_e32 v191, v191
	v_exp_f32_e32 v192, v192
	v_exp_f32_e32 v193, v193
	v_add_f32_e32 v240, v162, v163
	v_add_f32_e32 v240, v240, v164
	v_add_f32_e32 v240, v240, v165
	v_add_f32_e32 v240, v240, v166
	v_add_f32_e32 v240, v240, v167
	v_add_f32_e32 v240, v240, v168
	v_add_f32_e32 v240, v240, v169
	v_add_f32_e32 v240, v240, v170
	v_add_f32_e32 v240, v240, v171
	v_add_f32_e32 v240, v240, v172
	v_add_f32_e32 v240, v240, v173
	v_add_f32_e32 v240, v240, v174
	v_add_f32_e32 v240, v240, v175
	v_add_f32_e32 v240, v240, v176
	v_add_f32_e32 v240, v240, v177
	v_add_f32_e32 v240, v240, v178
	v_add_f32_e32 v240, v240, v179
	v_add_f32_e32 v240, v240, v180
	v_add_f32_e32 v240, v240, v181
	v_add_f32_e32 v240, v240, v182
	v_add_f32_e32 v240, v240, v183
	v_add_f32_e32 v240, v240, v184
	v_add_f32_e32 v240, v240, v185
	v_add_f32_e32 v240, v240, v186
	v_add_f32_e32 v240, v240, v187
	v_add_f32_e32 v240, v240, v188
	v_add_f32_e32 v240, v240, v189
	v_add_f32_e32 v240, v240, v190
	v_add_f32_e32 v240, v240, v191
	v_add_f32_e32 v240, v240, v192
	v_add_f32_e32 v240, v240, v193
	v_mov_b32_e32 v241, v240
	v_cvt_pk_bf16_f32 v162, v162, v163
	v_cvt_pk_bf16_f32 v163, v164, v165
	v_cvt_pk_bf16_f32 v164, v166, v167
	v_cvt_pk_bf16_f32 v165, v168, v169
	v_cvt_pk_bf16_f32 v166, v170, v171
	v_cvt_pk_bf16_f32 v167, v172, v173
	v_cvt_pk_bf16_f32 v168, v174, v175
	v_cvt_pk_bf16_f32 v169, v176, v177
	v_cvt_pk_bf16_f32 v178, v178, v179
	v_cvt_pk_bf16_f32 v179, v180, v181
	v_cvt_pk_bf16_f32 v180, v182, v183
	v_cvt_pk_bf16_f32 v181, v184, v185
	v_cvt_pk_bf16_f32 v182, v186, v187
	v_cvt_pk_bf16_f32 v183, v188, v189
	v_cvt_pk_bf16_f32 v184, v190, v191
	v_cvt_pk_bf16_f32 v185, v192, v193
	s_nop 1
	v_permlane32_swap_b32_e32 v240, v241
	v_permlane32_swap_b32_e32 v162, v164
	v_permlane32_swap_b32_e32 v163, v165
	v_permlane32_swap_b32_e32 v166, v168
	v_permlane32_swap_b32_e32 v167, v169
	v_permlane32_swap_b32_e32 v178, v180
	v_permlane32_swap_b32_e32 v179, v181
	v_permlane32_swap_b32_e32 v182, v184
	v_permlane32_swap_b32_e32 v183, v185
	v_add_f32_e32 v240, v240, v241
	v_add_f32_e32 v239, v239, v240
	s_barrier
	ds_read_b64_tr_b16 v[212:213], v237 offset:0
	ds_read_b64_tr_b16 v[214:215], v237 offset:4096
	ds_read_b64_tr_b16 v[216:217], v237 offset:8192
	ds_read_b64_tr_b16 v[218:219], v237 offset:12288
	ds_read_b64_tr_b16 v[220:221], v237 offset:16384
	ds_read_b64_tr_b16 v[222:223], v237 offset:20480
	ds_read_b64_tr_b16 v[224:225], v237 offset:24576
	ds_read_b64_tr_b16 v[226:227], v237 offset:28672
	ds_read_b64_tr_b16 v[170:171], v237 offset:512
	ds_read_b64_tr_b16 v[172:173], v237 offset:4608
	ds_read_b64_tr_b16 v[174:175], v237 offset:8704
	ds_read_b64_tr_b16 v[176:177], v237 offset:12800
	ds_read_b64_tr_b16 v[186:187], v237 offset:16896
	ds_read_b64_tr_b16 v[188:189], v237 offset:20992
	ds_read_b64_tr_b16 v[190:191], v237 offset:25088
	ds_read_b64_tr_b16 v[192:193], v237 offset:29184
	s_waitcnt lgkmcnt(8)
	v_mfma_f32_32x32x16_bf16 v[0:15], v[162:165], v[212:215], v[0:15]
	v_mfma_f32_32x32x16_bf16 v[0:15], v[166:169], v[216:219], v[0:15]
	v_mfma_f32_32x32x16_bf16 v[0:15], v[178:181], v[220:223], v[0:15]
	v_mfma_f32_32x32x16_bf16 v[0:15], v[182:185], v[224:227], v[0:15]
	ds_read_b64_tr_b16 v[212:213], v237 offset:1024
	ds_read_b64_tr_b16 v[214:215], v237 offset:5120
	ds_read_b64_tr_b16 v[216:217], v237 offset:9216
	ds_read_b64_tr_b16 v[218:219], v237 offset:13312
	ds_read_b64_tr_b16 v[220:221], v237 offset:17408
	ds_read_b64_tr_b16 v[222:223], v237 offset:21504
	ds_read_b64_tr_b16 v[224:225], v237 offset:25600
	ds_read_b64_tr_b16 v[226:227], v237 offset:29696
	s_waitcnt lgkmcnt(8)
	v_mfma_f32_32x32x16_bf16 v[16:31], v[162:165], v[170:173], v[16:31]
	v_mfma_f32_32x32x16_bf16 v[16:31], v[166:169], v[174:177], v[16:31]
	v_mfma_f32_32x32x16_bf16 v[16:31], v[178:181], v[186:189], v[16:31]
	v_mfma_f32_32x32x16_bf16 v[16:31], v[182:185], v[190:193], v[16:31]
	ds_read_b64_tr_b16 v[170:171], v237 offset:1536
	ds_read_b64_tr_b16 v[172:173], v237 offset:5632
	ds_read_b64_tr_b16 v[174:175], v237 offset:9728
	ds_read_b64_tr_b16 v[176:177], v237 offset:13824
	ds_read_b64_tr_b16 v[186:187], v237 offset:17920
	ds_read_b64_tr_b16 v[188:189], v237 offset:22016
	ds_read_b64_tr_b16 v[190:191], v237 offset:26112
	ds_read_b64_tr_b16 v[192:193], v237 offset:30208
	s_waitcnt lgkmcnt(8)
	v_mfma_f32_32x32x16_bf16 v[32:47], v[162:165], v[212:215], v[32:47]
	v_mfma_f32_32x32x16_bf16 v[32:47], v[166:169], v[216:219], v[32:47]
	v_mfma_f32_32x32x16_bf16 v[32:47], v[178:181], v[220:223], v[32:47]
	v_mfma_f32_32x32x16_bf16 v[32:47], v[182:185], v[224:227], v[32:47]
	ds_read_b64_tr_b16 v[212:213], v237 offset:2048
	ds_read_b64_tr_b16 v[214:215], v237 offset:6144
	ds_read_b64_tr_b16 v[216:217], v237 offset:10240
	ds_read_b64_tr_b16 v[218:219], v237 offset:14336
	ds_read_b64_tr_b16 v[220:221], v237 offset:18432
	ds_read_b64_tr_b16 v[222:223], v237 offset:22528
	ds_read_b64_tr_b16 v[224:225], v237 offset:26624
	ds_read_b64_tr_b16 v[226:227], v237 offset:30720
	s_waitcnt lgkmcnt(8)
	v_mfma_f32_32x32x16_bf16 v[48:63], v[162:165], v[170:173], v[48:63]
	v_mfma_f32_32x32x16_bf16 v[48:63], v[166:169], v[174:177], v[48:63]
	v_mfma_f32_32x32x16_bf16 v[48:63], v[178:181], v[186:189], v[48:63]
	v_mfma_f32_32x32x16_bf16 v[48:63], v[182:185], v[190:193], v[48:63]
	ds_read_b64_tr_b16 v[170:171], v237 offset:2560
	ds_read_b64_tr_b16 v[172:173], v237 offset:6656
	ds_read_b64_tr_b16 v[174:175], v237 offset:10752
	ds_read_b64_tr_b16 v[176:177], v237 offset:14848
	ds_read_b64_tr_b16 v[186:187], v237 offset:18944
	ds_read_b64_tr_b16 v[188:189], v237 offset:23040
	ds_read_b64_tr_b16 v[190:191], v237 offset:27136
	ds_read_b64_tr_b16 v[192:193], v237 offset:31232
	s_waitcnt lgkmcnt(8)
	v_mfma_f32_32x32x16_bf16 v[64:79], v[162:165], v[212:215], v[64:79]
	v_mfma_f32_32x32x16_bf16 v[64:79], v[166:169], v[216:219], v[64:79]
	v_mfma_f32_32x32x16_bf16 v[64:79], v[178:181], v[220:223], v[64:79]
	v_mfma_f32_32x32x16_bf16 v[64:79], v[182:185], v[224:227], v[64:79]
	ds_read_b64_tr_b16 v[212:213], v237 offset:3072
	ds_read_b64_tr_b16 v[214:215], v237 offset:7168
	ds_read_b64_tr_b16 v[216:217], v237 offset:11264
	ds_read_b64_tr_b16 v[218:219], v237 offset:15360
	ds_read_b64_tr_b16 v[220:221], v237 offset:19456
	ds_read_b64_tr_b16 v[222:223], v237 offset:23552
	ds_read_b64_tr_b16 v[224:225], v237 offset:27648
	ds_read_b64_tr_b16 v[226:227], v237 offset:31744
	s_waitcnt lgkmcnt(8)
	v_mfma_f32_32x32x16_bf16 v[80:95], v[162:165], v[170:173], v[80:95]
	v_mfma_f32_32x32x16_bf16 v[80:95], v[166:169], v[174:177], v[80:95]
	v_mfma_f32_32x32x16_bf16 v[80:95], v[178:181], v[186:189], v[80:95]
	v_mfma_f32_32x32x16_bf16 v[80:95], v[182:185], v[190:193], v[80:95]
	ds_read_b64_tr_b16 v[170:171], v237 offset:3584
	ds_read_b64_tr_b16 v[172:173], v237 offset:7680
	ds_read_b64_tr_b16 v[174:175], v237 offset:11776
	ds_read_b64_tr_b16 v[176:177], v237 offset:15872
	ds_read_b64_tr_b16 v[186:187], v237 offset:19968
	ds_read_b64_tr_b16 v[188:189], v237 offset:24064
	ds_read_b64_tr_b16 v[190:191], v237 offset:28160
	ds_read_b64_tr_b16 v[192:193], v237 offset:32256
	s_waitcnt lgkmcnt(8)
	v_mfma_f32_32x32x16_bf16 v[98:113], v[162:165], v[212:215], v[98:113]
	v_mfma_f32_32x32x16_bf16 v[98:113], v[166:169], v[216:219], v[98:113]
	v_mfma_f32_32x32x16_bf16 v[98:113], v[178:181], v[220:223], v[98:113]
	v_mfma_f32_32x32x16_bf16 v[98:113], v[182:185], v[224:227], v[98:113]
	ds_read_b128 v[212:215], v228 offset:0
	ds_read_b128 v[216:219], v228 offset:8192
	ds_read_b128 v[220:223], v229 offset:0
	ds_read_b128 v[224:227], v229 offset:8192
	s_waitcnt lgkmcnt(4)
	v_mfma_f32_32x32x16_bf16 v[114:129], v[162:165], v[170:173], v[114:129]
	v_mfma_f32_32x32x16_bf16 v[114:129], v[166:169], v[174:177], v[114:129]
	v_mfma_f32_32x32x16_bf16 v[114:129], v[178:181], v[186:189], v[114:129]
	v_mfma_f32_32x32x16_bf16 v[114:129], v[182:185], v[190:193], v[114:129]
	s_cmp_lt_u32 s13, 2
	s_cbranch_scc1 .Lap_noqk_B1
	s_waitcnt lgkmcnt(2)
	v_mfma_f32_32x32x16_bf16 v[162:177], v[212:215], v[130:133], 0
	v_mfma_f32_32x32x16_bf16 v[178:193], v[216:219], v[130:133], 0
	ds_read_b128 v[212:215], v230 offset:0
	ds_read_b128 v[216:219], v230 offset:8192
	s_waitcnt lgkmcnt(2)
	v_mfma_f32_32x32x16_bf16 v[162:177], v[220:223], v[134:137], v[162:177]
	v_mfma_f32_32x32x16_bf16 v[178:193], v[224:227], v[134:137], v[178:193]
	ds_read_b128 v[220:223], v231 offset:0
	ds_read_b128 v[224:227], v231 offset:8192
	s_waitcnt lgkmcnt(2)
	v_mfma_f32_32x32x16_bf16 v[162:177], v[212:215], v[138:141], v[162:177]
	v_mfma_f32_32x32x16_bf16 v[178:193], v[216:219], v[138:141], v[178:193]
	ds_read_b128 v[212:215], v232 offset:0
	ds_read_b128 v[216:219], v232 offset:8192
	s_waitcnt lgkmcnt(2)
	v_mfma_f32_32x32x16_bf16 v[162:177], v[220:223], v[142:145], v[162:177]
	v_mfma_f32_32x32x16_bf16 v[178:193], v[224:227], v[142:145], v[178:193]
	ds_read_b128 v[220:223], v233 offset:0
	ds_read_b128 v[224:227], v233 offset:8192
	s_waitcnt lgkmcnt(2)
	v_mfma_f32_32x32x16_bf16 v[162:177], v[212:215], v[146:149], v[162:177]
	v_mfma_f32_32x32x16_bf16 v[178:193], v[216:219], v[146:149], v[178:193]
	ds_read_b128 v[212:215], v234 offset:0
	ds_read_b128 v[216:219], v234 offset:8192
	s_waitcnt lgkmcnt(2)
	v_mfma_f32_32x32x16_bf16 v[162:177], v[220:223], v[150:153], v[162:177]
	v_mfma_f32_32x32x16_bf16 v[178:193], v[224:227], v[150:153], v[178:193]
	ds_read_b128 v[220:223], v235 offset:0
	ds_read_b128 v[224:227], v235 offset:8192
	s_waitcnt lgkmcnt(2)
	v_mfma_f32_32x32x16_bf16 v[162:177], v[212:215], v[154:157], v[162:177]
	v_mfma_f32_32x32x16_bf16 v[178:193], v[216:219], v[154:157], v[178:193]
	s_waitcnt lgkmcnt(0)
	v_mfma_f32_32x32x16_bf16 v[162:177], v[220:223], v[158:161], v[162:177]
	v_mfma_f32_32x32x16_bf16 v[178:193], v[224:227], v[158:161], v[178:193]
.Lap_noqk_B1:
	s_waitcnt lgkmcnt(0)
	s_nop 7
	s_nop 4
	s_waitcnt vmcnt(0)
	s_barrier
	s_sub_i32 s13, s13, 1
	s_cmp_gt_u32 s13, 0
	s_cbranch_scc1 .Lap_loopB
.Lap_epi:
	v_and_b32_e32 v240, 31, v96
	v_lshl_add_u32 v241, v240, 2, s50
	ds_write_b32 v241, v239 offset:128
	v_lshrrev_b32_e32 v241, 5, v96
	v_lshl_add_u32 v242, v241, 4, s50
	s_waitcnt lgkmcnt(0)
	ds_read_b128 v[212:215], v242 offset:128
	ds_read_b128 v[216:219], v242 offset:160
	ds_read_b128 v[220:223], v242 offset:192
	ds_read_b128 v[224:227], v242 offset:224
	s_lshl_b32 s37, s36, 5
	v_lshl_add_u32 v241, v241, 2, s37
	v_lshlrev_b32_e32 v241, 13, v241
	v_lshl_add_u32 v241, v240, 1, v241
	s_waitcnt lgkmcnt(0)
	v_rcp_f32_e32 v212, v212
	v_rcp_f32_e32 v213, v213
	v_rcp_f32_e32 v214, v214
	v_rcp_f32_e32 v215, v215
	v_rcp_f32_e32 v216, v216
	v_rcp_f32_e32 v217, v217
	v_rcp_f32_e32 v218, v218
	v_rcp_f32_e32 v219, v219
	v_rcp_f32_e32 v220, v220
	v_rcp_f32_e32 v221, v221
	v_rcp_f32_e32 v222, v222
	v_rcp_f32_e32 v223, v223
	v_rcp_f32_e32 v224, v224
	v_rcp_f32_e32 v225, v225
	v_rcp_f32_e32 v226, v226
	v_rcp_f32_e32 v227, v227
	s_nop 0
	v_mov_b32_e32 v240, v241
	v_mul_f32_e32 v162, v0, v212
	v_cvt_pk_bf16_f32 v162, v162, v162
	global_store_short v240, v162, s[22:23]
	v_mul_f32_e32 v163, v16, v212
	v_cvt_pk_bf16_f32 v163, v163, v163
	global_store_short v240, v163, s[22:23] offset:64
	v_mul_f32_e32 v164, v32, v212
	v_cvt_pk_bf16_f32 v164, v164, v164
	global_store_short v240, v164, s[22:23] offset:128
	v_mul_f32_e32 v165, v48, v212
	v_cvt_pk_bf16_f32 v165, v165, v165
	global_store_short v240, v165, s[22:23] offset:192
	v_mul_f32_e32 v166, v64, v212
	v_cvt_pk_bf16_f32 v166, v166, v166
	global_store_short v240, v166, s[22:23] offset:256
	v_mul_f32_e32 v167, v80, v212
	v_cvt_pk_bf16_f32 v167, v167, v167
	global_store_short v240, v167, s[22:23] offset:320
	v_mul_f32_e32 v168, v98, v212
	v_cvt_pk_bf16_f32 v168, v168, v168
	global_store_short v240, v168, s[22:23] offset:384
	v_mul_f32_e32 v169, v114, v212
	v_cvt_pk_bf16_f32 v169, v169, v169
	global_store_short v240, v169, s[22:23] offset:448
	v_add_u32_e32 v240, 0x2000, v241
	v_mul_f32_e32 v170, v1, v213
	v_cvt_pk_bf16_f32 v170, v170, v170
	global_store_short v240, v170, s[22:23]
	v_mul_f32_e32 v171, v17, v213
	v_cvt_pk_bf16_f32 v171, v171, v171
	global_store_short v240, v171, s[22:23] offset:64
	v_mul_f32_e32 v172, v33, v213
	v_cvt_pk_bf16_f32 v172, v172, v172
	global_store_short v240, v172, s[22:23] offset:128
	v_mul_f32_e32 v173, v49, v213
	v_cvt_pk_bf16_f32 v173, v173, v173
	global_store_short v240, v173, s[22:23] offset:192
	v_mul_f32_e32 v174, v65, v213
	v_cvt_pk_bf16_f32 v174, v174, v174
	global_store_short v240, v174, s[22:23] offset:256
	v_mul_f32_e32 v175, v81, v213
	v_cvt_pk_bf16_f32 v175, v175, v175
	global_store_short v240, v175, s[22:23] offset:320
	v_mul_f32_e32 v176, v99, v213
	v_cvt_pk_bf16_f32 v176, v176, v176
	global_store_short v240, v176, s[22:23] offset:384
	v_mul_f32_e32 v177, v115, v213
	v_cvt_pk_bf16_f32 v177, v177, v177
	global_store_short v240, v177, s[22:23] offset:448
	v_add_u32_e32 v240, 0x4000, v241
	v_mul_f32_e32 v178, v2, v214
	v_cvt_pk_bf16_f32 v178, v178, v178
	global_store_short v240, v178, s[22:23]
	v_mul_f32_e32 v179, v18, v214
	v_cvt_pk_bf16_f32 v179, v179, v179
	global_store_short v240, v179, s[22:23] offset:64
	v_mul_f32_e32 v180, v34, v214
	v_cvt_pk_bf16_f32 v180, v180, v180
	global_store_short v240, v180, s[22:23] offset:128
	v_mul_f32_e32 v181, v50, v214
	v_cvt_pk_bf16_f32 v181, v181, v181
	global_store_short v240, v181, s[22:23] offset:192
	v_mul_f32_e32 v182, v66, v214
	v_cvt_pk_bf16_f32 v182, v182, v182
	global_store_short v240, v182, s[22:23] offset:256
	v_mul_f32_e32 v183, v82, v214
	v_cvt_pk_bf16_f32 v183, v183, v183
	global_store_short v240, v183, s[22:23] offset:320
	v_mul_f32_e32 v184, v100, v214
	v_cvt_pk_bf16_f32 v184, v184, v184
	global_store_short v240, v184, s[22:23] offset:384
	v_mul_f32_e32 v185, v116, v214
	v_cvt_pk_bf16_f32 v185, v185, v185
	global_store_short v240, v185, s[22:23] offset:448
	v_add_u32_e32 v240, 0x6000, v241
	v_mul_f32_e32 v186, v3, v215
	v_cvt_pk_bf16_f32 v186, v186, v186
	global_store_short v240, v186, s[22:23]
	v_mul_f32_e32 v187, v19, v215
	v_cvt_pk_bf16_f32 v187, v187, v187
	global_store_short v240, v187, s[22:23] offset:64
	v_mul_f32_e32 v188, v35, v215
	v_cvt_pk_bf16_f32 v188, v188, v188
	global_store_short v240, v188, s[22:23] offset:128
	v_mul_f32_e32 v189, v51, v215
	v_cvt_pk_bf16_f32 v189, v189, v189
	global_store_short v240, v189, s[22:23] offset:192
	v_mul_f32_e32 v190, v67, v215
	v_cvt_pk_bf16_f32 v190, v190, v190
	global_store_short v240, v190, s[22:23] offset:256
	v_mul_f32_e32 v191, v83, v215
	v_cvt_pk_bf16_f32 v191, v191, v191
	global_store_short v240, v191, s[22:23] offset:320
	v_mul_f32_e32 v192, v101, v215
	v_cvt_pk_bf16_f32 v192, v192, v192
	global_store_short v240, v192, s[22:23] offset:384
	v_mul_f32_e32 v193, v117, v215
	v_cvt_pk_bf16_f32 v193, v193, v193
	global_store_short v240, v193, s[22:23] offset:448
	v_add_u32_e32 v240, 0x10000, v241
	v_mul_f32_e32 v162, v4, v216
	v_cvt_pk_bf16_f32 v162, v162, v162
	global_store_short v240, v162, s[22:23]
	v_mul_f32_e32 v163, v20, v216
	v_cvt_pk_bf16_f32 v163, v163, v163
	global_store_short v240, v163, s[22:23] offset:64
	v_mul_f32_e32 v164, v36, v216
	v_cvt_pk_bf16_f32 v164, v164, v164
	global_store_short v240, v164, s[22:23] offset:128
	v_mul_f32_e32 v165, v52, v216
	v_cvt_pk_bf16_f32 v165, v165, v165
	global_store_short v240, v165, s[22:23] offset:192
	v_mul_f32_e32 v166, v68, v216
	v_cvt_pk_bf16_f32 v166, v166, v166
	global_store_short v240, v166, s[22:23] offset:256
	v_mul_f32_e32 v167, v84, v216
	v_cvt_pk_bf16_f32 v167, v167, v167
	global_store_short v240, v167, s[22:23] offset:320
	v_mul_f32_e32 v168, v102, v216
	v_cvt_pk_bf16_f32 v168, v168, v168
	global_store_short v240, v168, s[22:23] offset:384
	v_mul_f32_e32 v169, v118, v216
	v_cvt_pk_bf16_f32 v169, v169, v169
	global_store_short v240, v169, s[22:23] offset:448
	v_add_u32_e32 v240, 0x12000, v241
	v_mul_f32_e32 v170, v5, v217
	v_cvt_pk_bf16_f32 v170, v170, v170
	global_store_short v240, v170, s[22:23]
	v_mul_f32_e32 v171, v21, v217
	v_cvt_pk_bf16_f32 v171, v171, v171
	global_store_short v240, v171, s[22:23] offset:64
	v_mul_f32_e32 v172, v37, v217
	v_cvt_pk_bf16_f32 v172, v172, v172
	global_store_short v240, v172, s[22:23] offset:128
	v_mul_f32_e32 v173, v53, v217
	v_cvt_pk_bf16_f32 v173, v173, v173
	global_store_short v240, v173, s[22:23] offset:192
	v_mul_f32_e32 v174, v69, v217
	v_cvt_pk_bf16_f32 v174, v174, v174
	global_store_short v240, v174, s[22:23] offset:256
	v_mul_f32_e32 v175, v85, v217
	v_cvt_pk_bf16_f32 v175, v175, v175
	global_store_short v240, v175, s[22:23] offset:320
	v_mul_f32_e32 v176, v103, v217
	v_cvt_pk_bf16_f32 v176, v176, v176
	global_store_short v240, v176, s[22:23] offset:384
	v_mul_f32_e32 v177, v119, v217
	v_cvt_pk_bf16_f32 v177, v177, v177
	global_store_short v240, v177, s[22:23] offset:448
	v_add_u32_e32 v240, 0x14000, v241
	v_mul_f32_e32 v178, v6, v218
	v_cvt_pk_bf16_f32 v178, v178, v178
	global_store_short v240, v178, s[22:23]
	v_mul_f32_e32 v179, v22, v218
	v_cvt_pk_bf16_f32 v179, v179, v179
	global_store_short v240, v179, s[22:23] offset:64
	v_mul_f32_e32 v180, v38, v218
	v_cvt_pk_bf16_f32 v180, v180, v180
	global_store_short v240, v180, s[22:23] offset:128
	v_mul_f32_e32 v181, v54, v218
	v_cvt_pk_bf16_f32 v181, v181, v181
	global_store_short v240, v181, s[22:23] offset:192
	v_mul_f32_e32 v182, v70, v218
	v_cvt_pk_bf16_f32 v182, v182, v182
	global_store_short v240, v182, s[22:23] offset:256
	v_mul_f32_e32 v183, v86, v218
	v_cvt_pk_bf16_f32 v183, v183, v183
	global_store_short v240, v183, s[22:23] offset:320
	v_mul_f32_e32 v184, v104, v218
	v_cvt_pk_bf16_f32 v184, v184, v184
	global_store_short v240, v184, s[22:23] offset:384
	v_mul_f32_e32 v185, v120, v218
	v_cvt_pk_bf16_f32 v185, v185, v185
	global_store_short v240, v185, s[22:23] offset:448
	v_add_u32_e32 v240, 0x16000, v241
	v_mul_f32_e32 v186, v7, v219
	v_cvt_pk_bf16_f32 v186, v186, v186
	global_store_short v240, v186, s[22:23]
	v_mul_f32_e32 v187, v23, v219
	v_cvt_pk_bf16_f32 v187, v187, v187
	global_store_short v240, v187, s[22:23] offset:64
	v_mul_f32_e32 v188, v39, v219
	v_cvt_pk_bf16_f32 v188, v188, v188
	global_store_short v240, v188, s[22:23] offset:128
	v_mul_f32_e32 v189, v55, v219
	v_cvt_pk_bf16_f32 v189, v189, v189
	global_store_short v240, v189, s[22:23] offset:192
	v_mul_f32_e32 v190, v71, v219
	v_cvt_pk_bf16_f32 v190, v190, v190
	global_store_short v240, v190, s[22:23] offset:256
	v_mul_f32_e32 v191, v87, v219
	v_cvt_pk_bf16_f32 v191, v191, v191
	global_store_short v240, v191, s[22:23] offset:320
	v_mul_f32_e32 v192, v105, v219
	v_cvt_pk_bf16_f32 v192, v192, v192
	global_store_short v240, v192, s[22:23] offset:384
	v_mul_f32_e32 v193, v121, v219
	v_cvt_pk_bf16_f32 v193, v193, v193
	global_store_short v240, v193, s[22:23] offset:448
	v_add_u32_e32 v240, 0x20000, v241
	v_mul_f32_e32 v162, v8, v220
	v_cvt_pk_bf16_f32 v162, v162, v162
	global_store_short v240, v162, s[22:23]
	v_mul_f32_e32 v163, v24, v220
	v_cvt_pk_bf16_f32 v163, v163, v163
	global_store_short v240, v163, s[22:23] offset:64
	v_mul_f32_e32 v164, v40, v220
	v_cvt_pk_bf16_f32 v164, v164, v164
	global_store_short v240, v164, s[22:23] offset:128
	v_mul_f32_e32 v165, v56, v220
	v_cvt_pk_bf16_f32 v165, v165, v165
	global_store_short v240, v165, s[22:23] offset:192
	v_mul_f32_e32 v166, v72, v220
	v_cvt_pk_bf16_f32 v166, v166, v166
	global_store_short v240, v166, s[22:23] offset:256
	v_mul_f32_e32 v167, v88, v220
	v_cvt_pk_bf16_f32 v167, v167, v167
	global_store_short v240, v167, s[22:23] offset:320
	v_mul_f32_e32 v168, v106, v220
	v_cvt_pk_bf16_f32 v168, v168, v168
	global_store_short v240, v168, s[22:23] offset:384
	v_mul_f32_e32 v169, v122, v220
	v_cvt_pk_bf16_f32 v169, v169, v169
	global_store_short v240, v169, s[22:23] offset:448
	v_add_u32_e32 v240, 0x22000, v241
	v_mul_f32_e32 v170, v9, v221
	v_cvt_pk_bf16_f32 v170, v170, v170
	global_store_short v240, v170, s[22:23]
	v_mul_f32_e32 v171, v25, v221
	v_cvt_pk_bf16_f32 v171, v171, v171
	global_store_short v240, v171, s[22:23] offset:64
	v_mul_f32_e32 v172, v41, v221
	v_cvt_pk_bf16_f32 v172, v172, v172
	global_store_short v240, v172, s[22:23] offset:128
	v_mul_f32_e32 v173, v57, v221
	v_cvt_pk_bf16_f32 v173, v173, v173
	global_store_short v240, v173, s[22:23] offset:192
	v_mul_f32_e32 v174, v73, v221
	v_cvt_pk_bf16_f32 v174, v174, v174
	global_store_short v240, v174, s[22:23] offset:256
	v_mul_f32_e32 v175, v89, v221
	v_cvt_pk_bf16_f32 v175, v175, v175
	global_store_short v240, v175, s[22:23] offset:320
	v_mul_f32_e32 v176, v107, v221
	v_cvt_pk_bf16_f32 v176, v176, v176
	global_store_short v240, v176, s[22:23] offset:384
	v_mul_f32_e32 v177, v123, v221
	v_cvt_pk_bf16_f32 v177, v177, v177
	global_store_short v240, v177, s[22:23] offset:448
	v_add_u32_e32 v240, 0x24000, v241
	v_mul_f32_e32 v178, v10, v222
	v_cvt_pk_bf16_f32 v178, v178, v178
	global_store_short v240, v178, s[22:23]
	v_mul_f32_e32 v179, v26, v222
	v_cvt_pk_bf16_f32 v179, v179, v179
	global_store_short v240, v179, s[22:23] offset:64
	v_mul_f32_e32 v180, v42, v222
	v_cvt_pk_bf16_f32 v180, v180, v180
	global_store_short v240, v180, s[22:23] offset:128
	v_mul_f32_e32 v181, v58, v222
	v_cvt_pk_bf16_f32 v181, v181, v181
	global_store_short v240, v181, s[22:23] offset:192
	v_mul_f32_e32 v182, v74, v222
	v_cvt_pk_bf16_f32 v182, v182, v182
	global_store_short v240, v182, s[22:23] offset:256
	v_mul_f32_e32 v183, v90, v222
	v_cvt_pk_bf16_f32 v183, v183, v183
	global_store_short v240, v183, s[22:23] offset:320
	v_mul_f32_e32 v184, v108, v222
	v_cvt_pk_bf16_f32 v184, v184, v184
	global_store_short v240, v184, s[22:23] offset:384
	v_mul_f32_e32 v185, v124, v222
	v_cvt_pk_bf16_f32 v185, v185, v185
	global_store_short v240, v185, s[22:23] offset:448
	v_add_u32_e32 v240, 0x26000, v241
	v_mul_f32_e32 v186, v11, v223
	v_cvt_pk_bf16_f32 v186, v186, v186
	global_store_short v240, v186, s[22:23]
	v_mul_f32_e32 v187, v27, v223
	v_cvt_pk_bf16_f32 v187, v187, v187
	global_store_short v240, v187, s[22:23] offset:64
	v_mul_f32_e32 v188, v43, v223
	v_cvt_pk_bf16_f32 v188, v188, v188
	global_store_short v240, v188, s[22:23] offset:128
	v_mul_f32_e32 v189, v59, v223
	v_cvt_pk_bf16_f32 v189, v189, v189
	global_store_short v240, v189, s[22:23] offset:192
	v_mul_f32_e32 v190, v75, v223
	v_cvt_pk_bf16_f32 v190, v190, v190
	global_store_short v240, v190, s[22:23] offset:256
	v_mul_f32_e32 v191, v91, v223
	v_cvt_pk_bf16_f32 v191, v191, v191
	global_store_short v240, v191, s[22:23] offset:320
	v_mul_f32_e32 v192, v109, v223
	v_cvt_pk_bf16_f32 v192, v192, v192
	global_store_short v240, v192, s[22:23] offset:384
	v_mul_f32_e32 v193, v125, v223
	v_cvt_pk_bf16_f32 v193, v193, v193
	global_store_short v240, v193, s[22:23] offset:448
	v_add_u32_e32 v240, 0x30000, v241
	v_mul_f32_e32 v162, v12, v224
	v_cvt_pk_bf16_f32 v162, v162, v162
	global_store_short v240, v162, s[22:23]
	v_mul_f32_e32 v163, v28, v224
	v_cvt_pk_bf16_f32 v163, v163, v163
	global_store_short v240, v163, s[22:23] offset:64
	v_mul_f32_e32 v164, v44, v224
	v_cvt_pk_bf16_f32 v164, v164, v164
	global_store_short v240, v164, s[22:23] offset:128
	v_mul_f32_e32 v165, v60, v224
	v_cvt_pk_bf16_f32 v165, v165, v165
	global_store_short v240, v165, s[22:23] offset:192
	v_mul_f32_e32 v166, v76, v224
	v_cvt_pk_bf16_f32 v166, v166, v166
	global_store_short v240, v166, s[22:23] offset:256
	v_mul_f32_e32 v167, v92, v224
	v_cvt_pk_bf16_f32 v167, v167, v167
	global_store_short v240, v167, s[22:23] offset:320
	v_mul_f32_e32 v168, v110, v224
	v_cvt_pk_bf16_f32 v168, v168, v168
	global_store_short v240, v168, s[22:23] offset:384
	v_mul_f32_e32 v169, v126, v224
	v_cvt_pk_bf16_f32 v169, v169, v169
	global_store_short v240, v169, s[22:23] offset:448
	v_add_u32_e32 v240, 0x32000, v241
	v_mul_f32_e32 v170, v13, v225
	v_cvt_pk_bf16_f32 v170, v170, v170
	global_store_short v240, v170, s[22:23]
	v_mul_f32_e32 v171, v29, v225
	v_cvt_pk_bf16_f32 v171, v171, v171
	global_store_short v240, v171, s[22:23] offset:64
	v_mul_f32_e32 v172, v45, v225
	v_cvt_pk_bf16_f32 v172, v172, v172
	global_store_short v240, v172, s[22:23] offset:128
	v_mul_f32_e32 v173, v61, v225
	v_cvt_pk_bf16_f32 v173, v173, v173
	global_store_short v240, v173, s[22:23] offset:192
	v_mul_f32_e32 v174, v77, v225
	v_cvt_pk_bf16_f32 v174, v174, v174
	global_store_short v240, v174, s[22:23] offset:256
	v_mul_f32_e32 v175, v93, v225
	v_cvt_pk_bf16_f32 v175, v175, v175
	global_store_short v240, v175, s[22:23] offset:320
	v_mul_f32_e32 v176, v111, v225
	v_cvt_pk_bf16_f32 v176, v176, v176
	global_store_short v240, v176, s[22:23] offset:384
	v_mul_f32_e32 v177, v127, v225
	v_cvt_pk_bf16_f32 v177, v177, v177
	global_store_short v240, v177, s[22:23] offset:448
	v_add_u32_e32 v240, 0x34000, v241
	v_mul_f32_e32 v178, v14, v226
	v_cvt_pk_bf16_f32 v178, v178, v178
	global_store_short v240, v178, s[22:23]
	v_mul_f32_e32 v179, v30, v226
	v_cvt_pk_bf16_f32 v179, v179, v179
	global_store_short v240, v179, s[22:23] offset:64
	v_mul_f32_e32 v180, v46, v226
	v_cvt_pk_bf16_f32 v180, v180, v180
	global_store_short v240, v180, s[22:23] offset:128
	v_mul_f32_e32 v181, v62, v226
	v_cvt_pk_bf16_f32 v181, v181, v181
	global_store_short v240, v181, s[22:23] offset:192
	v_mul_f32_e32 v182, v78, v226
	v_cvt_pk_bf16_f32 v182, v182, v182
	global_store_short v240, v182, s[22:23] offset:256
	v_mul_f32_e32 v183, v94, v226
	v_cvt_pk_bf16_f32 v183, v183, v183
	global_store_short v240, v183, s[22:23] offset:320
	v_mul_f32_e32 v184, v112, v226
	v_cvt_pk_bf16_f32 v184, v184, v184
	global_store_short v240, v184, s[22:23] offset:384
	v_mul_f32_e32 v185, v128, v226
	v_cvt_pk_bf16_f32 v185, v185, v185
	global_store_short v240, v185, s[22:23] offset:448
	v_add_u32_e32 v240, 0x36000, v241
	v_mul_f32_e32 v186, v15, v227
	v_cvt_pk_bf16_f32 v186, v186, v186
	global_store_short v240, v186, s[22:23]
	v_mul_f32_e32 v187, v31, v227
	v_cvt_pk_bf16_f32 v187, v187, v187
	global_store_short v240, v187, s[22:23] offset:64
	v_mul_f32_e32 v188, v47, v227
	v_cvt_pk_bf16_f32 v188, v188, v188
	global_store_short v240, v188, s[22:23] offset:128
	v_mul_f32_e32 v189, v63, v227
	v_cvt_pk_bf16_f32 v189, v189, v189
	global_store_short v240, v189, s[22:23] offset:192
	v_mul_f32_e32 v190, v79, v227
	v_cvt_pk_bf16_f32 v190, v190, v190
	global_store_short v240, v190, s[22:23] offset:256
	v_mul_f32_e32 v191, v95, v227
	v_cvt_pk_bf16_f32 v191, v191, v191
	global_store_short v240, v191, s[22:23] offset:320
	v_mul_f32_e32 v192, v113, v227
	v_cvt_pk_bf16_f32 v192, v192, v192
	global_store_short v240, v192, s[22:23] offset:384
	v_mul_f32_e32 v193, v129, v227
	v_cvt_pk_bf16_f32 v193, v193, v193
	global_store_short v240, v193, s[22:23] offset:448
	s_cmp_ge_u32 s36, 4
	s_cbranch_scc1 .Lap_fin
	s_barrier
.Lap_fin:
	s_waitcnt lgkmcnt(0)
	s_barrier
	s_brev_b32 s30, 64
	v_readlane_b32 s31, v254, 63
	s_movk_i32 s61, 0x1000
	s_mov_b64 s[6:7], 0
